# DMA issues spread among MFMA groups in all 25 GEMM k-loops (incl. the pointer-bump PLE loops)
# speedup vs baseline: 1.0117x; 1.0028x over previous
; DEV int stage_next(int s) { return (s == 2 * GS_STAGE) ? 0 : s + GS_STAGE; }
; template <int WAIT0>
; DEV void gk_main(f32x16 (&acc)[2][2], const GTile& t, int s0) {
;     ...
;   vm_wait_bar<WAIT0>();
;   int stc = s0, std_ = stage_next(stage_next(s0));
; #pragma nounroll
;   for (int kt = 0; kt < nk - 2; ++kt) {
;     GK_DMA(std_, kt + 2);
;     GK_COMPUTE(stc);
;     vm_wait_bar<6>();
;     stc = stage_next(stc); std_ = stage_next(std_);
;   }
.LBB0_276:
	s_add_i32 s12, s10, s11
	s_mov_b32 s98, s12
	s_mov_b64 s[100:101], s[6:7]
	s_add_i32 s12, s3, 0
	v_add_u32_e32 v252, s12, v82
	v_add_u32_e32 v253, s12, v83
	ds_read_b128 v[84:87], v252
	ds_read_b128 v[88:91], v252 offset:4096
	ds_read_b128 v[92:95], v253 offset:16384
	ds_read_b128 v[96:99], v253 offset:20480
	s_waitcnt lgkmcnt(0)
	v_add_u32_e32 v252, s12, v80
	v_add_u32_e32 v253, s12, v81
	ds_read_b128 v[236:239], v252
	ds_read_b128 v[240:243], v252 offset:4096
	ds_read_b128 v[244:247], v253 offset:16384
	ds_read_b128 v[248:251], v253 offset:20480
	v_mfma_f32_32x32x16_bf16 v[48:63], v[92:95], v[84:87], v[48:63]
	v_mfma_f32_32x32x16_bf16 v[16:31], v[92:95], v[88:91], v[16:31]
	s_mov_b32 m0, s98
	v_lshl_add_u64 v[254:255], v[74:75], 0, s[100:101]
	global_load_lds_dwordx4 v[254:255], off
	v_mfma_f32_32x32x16_bf16 v[32:47], v[96:99], v[84:87], v[32:47]
	v_mfma_f32_32x32x16_bf16 v[0:15], v[96:99], v[88:91], v[0:15]
	s_add_i32 m0, s98, 0x2000
	v_lshl_add_u64 v[254:255], v[72:73], 0, s[100:101]
	global_load_lds_dwordx4 v[254:255], off
	s_waitcnt lgkmcnt(0)
	v_add_u32_e32 v252, s12, v78
	v_add_u32_e32 v253, s12, v79
	ds_read_b128 v[84:87], v252
	ds_read_b128 v[88:91], v252 offset:4096
	ds_read_b128 v[92:95], v253 offset:16384
	ds_read_b128 v[96:99], v253 offset:20480
	v_mfma_f32_32x32x16_bf16 v[48:63], v[244:247], v[236:239], v[48:63]
	v_mfma_f32_32x32x16_bf16 v[16:31], v[244:247], v[240:243], v[16:31]
	s_add_i32 m0, s98, 0x4000
	v_lshl_add_u64 v[254:255], v[70:71], 0, s[100:101]
	global_load_lds_dwordx4 v[254:255], off
	v_mfma_f32_32x32x16_bf16 v[32:47], v[248:251], v[236:239], v[32:47]
	v_mfma_f32_32x32x16_bf16 v[0:15], v[248:251], v[240:243], v[0:15]
	s_add_i32 m0, s98, 0x6000
	v_lshl_add_u64 v[254:255], v[68:69], 0, s[100:101]
	global_load_lds_dwordx4 v[254:255], off
	s_waitcnt lgkmcnt(0)
	v_add_u32_e32 v252, s12, v76
	v_add_u32_e32 v253, s12, v77
	ds_read_b128 v[236:239], v252
	ds_read_b128 v[240:243], v252 offset:4096
	ds_read_b128 v[244:247], v253 offset:16384
	ds_read_b128 v[248:251], v253 offset:20480
	v_mfma_f32_32x32x16_bf16 v[48:63], v[92:95], v[84:87], v[48:63]
	v_mfma_f32_32x32x16_bf16 v[16:31], v[92:95], v[88:91], v[16:31]
	s_add_i32 m0, s98, 0x8000
	v_lshl_add_u64 v[254:255], v[66:67], 0, s[100:101]
	global_load_lds_dwordx4 v[254:255], off
	v_mfma_f32_32x32x16_bf16 v[32:47], v[96:99], v[84:87], v[32:47]
	v_mfma_f32_32x32x16_bf16 v[0:15], v[96:99], v[88:91], v[0:15]
	s_add_i32 m0, s98, 0xa000
	v_lshl_add_u64 v[254:255], v[64:65], 0, s[100:101]
	global_load_lds_dwordx4 v[254:255], off
	s_add_i32 s12, s3, 0xc000
	s_cmp_lg_u32 s3, 0x18000
	s_cselect_b32 s3, s12, 0
	s_waitcnt lgkmcnt(0)
	v_mfma_f32_32x32x16_bf16 v[48:63], v[244:247], v[236:239], v[48:63]
	s_add_i32 s12, s11, 0xc000
	s_cmp_lg_u32 s11, 0x18000
	s_waitcnt vmcnt(6) lgkmcnt(0)
	s_barrier
	s_cselect_b32 s11, s12, 0
	s_add_u32 s6, s6, 0x80
	v_mfma_f32_32x32x16_bf16 v[16:31], v[244:247], v[240:243], v[16:31]
	s_addc_u32 s7, s7, 0
	s_cmpk_lg_i32 s6, 0x700
	v_mfma_f32_32x32x16_bf16 v[32:47], v[248:251], v[236:239], v[32:47]
	v_mfma_f32_32x32x16_bf16 v[0:15], v[248:251], v[240:243], v[0:15]
	s_cbranch_scc1 .LBB0_276
; DEV int stage_next(int s) { return (s == 2 * GS_STAGE) ? 0 : s + GS_STAGE; }
; template <int WAIT0>
; DEV void gk_main(f32x16 (&acc)[2][2], const GTile& t, int s0) {
;     ...
;   GK_COMPUTE(stc);
;   vm_wait_bar<0>();
;   stc = stage_next(stc);
;   GK_COMPUTE(stc);
;   vm_wait_bar<0>();
	s_add_i32 s6, s3, 0
	v_add_u32_e32 v84, s6, v83
	ds_read_b128 v[64:67], v84 offset:16384
	v_add_u32_e32 v72, s6, v82
	ds_read_b128 v[68:71], v72
	ds_read_b128 v[72:75], v72 offset:4096
	s_waitcnt lgkmcnt(0)
	v_mfma_f32_32x32x16_bf16 v[48:63], v[64:67], v[68:71], v[48:63]
	v_mfma_f32_32x32x16_bf16 v[16:31], v[64:67], v[72:75], v[16:31]
	ds_read_b128 v[64:67], v84 offset:20480
	v_add_u32_e32 v84, s6, v81
	s_waitcnt lgkmcnt(0)
	v_mfma_f32_32x32x16_bf16 v[32:47], v[64:67], v[68:71], v[32:47]
	v_mfma_f32_32x32x16_bf16 v[0:15], v[64:67], v[72:75], v[0:15]
	ds_read_b128 v[64:67], v84 offset:16384
	v_add_u32_e32 v72, s6, v80
	ds_read_b128 v[68:71], v72
	ds_read_b128 v[72:75], v72 offset:4096
	s_waitcnt lgkmcnt(0)
	v_mfma_f32_32x32x16_bf16 v[48:63], v[64:67], v[68:71], v[48:63]
	v_mfma_f32_32x32x16_bf16 v[16:31], v[64:67], v[72:75], v[16:31]
	ds_read_b128 v[64:67], v84 offset:20480
	v_add_u32_e32 v84, s6, v79
	s_waitcnt lgkmcnt(0)
	v_mfma_f32_32x32x16_bf16 v[32:47], v[64:67], v[68:71], v[32:47]
	v_mfma_f32_32x32x16_bf16 v[0:15], v[64:67], v[72:75], v[0:15]
	ds_read_b128 v[64:67], v84 offset:16384
	v_add_u32_e32 v72, s6, v78
	ds_read_b128 v[68:71], v72
	ds_read_b128 v[72:75], v72 offset:4096
	s_waitcnt lgkmcnt(0)
	v_mfma_f32_32x32x16_bf16 v[48:63], v[64:67], v[68:71], v[48:63]
	v_mfma_f32_32x32x16_bf16 v[16:31], v[64:67], v[72:75], v[16:31]
	ds_read_b128 v[64:67], v84 offset:20480
	v_add_u32_e32 v84, s6, v77
	s_waitcnt lgkmcnt(0)
	v_mfma_f32_32x32x16_bf16 v[32:47], v[64:67], v[68:71], v[32:47]
	v_mfma_f32_32x32x16_bf16 v[0:15], v[64:67], v[72:75], v[0:15]
	ds_read_b128 v[64:67], v84 offset:16384
	v_add_u32_e32 v72, s6, v76
	ds_read_b128 v[68:71], v72
	ds_read_b128 v[72:75], v72 offset:4096
	s_add_i32 s6, s3, 0xc000
	s_cmp_lg_u32 s3, 0x18000
	s_cselect_b32 s3, s6, 0
	s_waitcnt lgkmcnt(0)
	v_mfma_f32_32x32x16_bf16 v[48:63], v[64:67], v[68:71], v[48:63]
	s_add_i32 s3, s3, 0
	v_add_u32_e32 v83, s3, v83
	v_add_u32_e32 v81, s3, v81
	v_add_u32_e32 v79, s3, v79
	v_add_u32_e32 v77, s3, v77
	s_mov_b64 s[6:7], 0
	v_mfma_f32_32x32x16_bf16 v[16:31], v[64:67], v[72:75], v[16:31]
	ds_read_b128 v[64:67], v84 offset:20480
	s_waitcnt vmcnt(0) lgkmcnt(0)
	s_barrier
	s_waitcnt lgkmcnt(0)
	v_mfma_f32_32x32x16_bf16 v[32:47], v[64:67], v[68:71], v[32:47]
	v_mfma_f32_32x32x16_bf16 v[0:15], v[64:67], v[72:75], v[0:15]
	ds_read_b128 v[64:67], v83 offset:16384
	v_add_u32_e32 v72, s3, v82
	ds_read_b128 v[68:71], v72
	ds_read_b128 v[72:75], v72 offset:4096
	s_waitcnt lgkmcnt(0)
	v_mfma_f32_32x32x16_bf16 v[48:63], v[64:67], v[68:71], v[48:63]
	v_mfma_f32_32x32x16_bf16 v[16:31], v[64:67], v[72:75], v[16:31]
	ds_read_b128 v[64:67], v83 offset:20480
	s_waitcnt lgkmcnt(0)
	v_mfma_f32_32x32x16_bf16 v[32:47], v[64:67], v[68:71], v[32:47]
	v_mfma_f32_32x32x16_bf16 v[0:15], v[64:67], v[72:75], v[0:15]
	ds_read_b128 v[64:67], v81 offset:16384
	v_add_u32_e32 v72, s3, v80
	ds_read_b128 v[68:71], v72
	ds_read_b128 v[72:75], v72 offset:4096
	s_waitcnt lgkmcnt(0)
	v_mfma_f32_32x32x16_bf16 v[48:63], v[64:67], v[68:71], v[48:63]
	v_mfma_f32_32x32x16_bf16 v[16:31], v[64:67], v[72:75], v[16:31]
	ds_read_b128 v[64:67], v81 offset:20480
	s_waitcnt lgkmcnt(0)
	v_mfma_f32_32x32x16_bf16 v[32:47], v[64:67], v[68:71], v[32:47]
	v_mfma_f32_32x32x16_bf16 v[0:15], v[64:67], v[72:75], v[0:15]
	ds_read_b128 v[64:67], v79 offset:16384
	v_add_u32_e32 v72, s3, v78
	ds_read_b128 v[68:71], v72
	ds_read_b128 v[72:75], v72 offset:4096
	s_waitcnt lgkmcnt(0)
	v_mfma_f32_32x32x16_bf16 v[48:63], v[64:67], v[68:71], v[48:63]
	v_mfma_f32_32x32x16_bf16 v[16:31], v[64:67], v[72:75], v[16:31]
	ds_read_b128 v[64:67], v79 offset:20480
	s_waitcnt lgkmcnt(0)
	v_mfma_f32_32x32x16_bf16 v[32:47], v[64:67], v[68:71], v[32:47]
	v_mfma_f32_32x32x16_bf16 v[0:15], v[64:67], v[72:75], v[0:15]
	ds_read_b128 v[64:67], v77 offset:16384
	v_add_u32_e32 v72, s3, v76
	ds_read_b128 v[68:71], v72
	ds_read_b128 v[72:75], v72 offset:4096
	s_waitcnt lgkmcnt(0)
	v_mfma_f32_32x32x16_bf16 v[48:63], v[64:67], v[68:71], v[48:63]
	v_mfma_f32_32x32x16_bf16 v[16:31], v[64:67], v[72:75], v[16:31]
	ds_read_b128 v[64:67], v77 offset:20480
	s_waitcnt vmcnt(0) lgkmcnt(0)
	s_barrier
	s_waitcnt lgkmcnt(0)
	v_mfma_f32_32x32x16_bf16 v[32:47], v[64:67], v[68:71], v[32:47]
	v_mfma_f32_32x32x16_bf16 v[0:15], v[64:67], v[72:75], v[0:15]

; DEV int stage_next(int s) { return (s == 2 * GS_STAGE) ? 0 : s + GS_STAGE; }
; template <int WAIT0>
; DEV void gk_main(f32x16 (&acc)[2][2], const GTile& t, int s0) {
;     ...
;   vm_wait_bar<WAIT0>();
;   int stc = s0, std_ = stage_next(stage_next(s0));
; #pragma nounroll
;   for (int kt = 0; kt < nk - 2; ++kt) {
;     GK_DMA(std_, kt + 2);
;     GK_COMPUTE(stc);
;     vm_wait_bar<6>();
;     stc = stage_next(stc); std_ = stage_next(std_);
;   }
.LBB0_280:
	s_add_i32 s12, s10, s11
	s_mov_b32 s98, s12
	s_mov_b64 s[100:101], s[6:7]
	s_add_i32 s12, s3, 0
	v_add_u32_e32 v252, s12, v82
	v_add_u32_e32 v253, s12, v83
	ds_read_b128 v[84:87], v252
	ds_read_b128 v[88:91], v252 offset:4096
	ds_read_b128 v[92:95], v253 offset:16384
	ds_read_b128 v[96:99], v253 offset:20480
	s_waitcnt lgkmcnt(0)
	v_add_u32_e32 v252, s12, v80
	v_add_u32_e32 v253, s12, v81
	ds_read_b128 v[236:239], v252
	ds_read_b128 v[240:243], v252 offset:4096
	ds_read_b128 v[244:247], v253 offset:16384
	ds_read_b128 v[248:251], v253 offset:20480
	v_mfma_f32_32x32x16_bf16 v[48:63], v[92:95], v[84:87], v[48:63]
	v_mfma_f32_32x32x16_bf16 v[16:31], v[92:95], v[88:91], v[16:31]
	s_mov_b32 m0, s98
	v_lshl_add_u64 v[254:255], v[74:75], 0, s[100:101]
	global_load_lds_dwordx4 v[254:255], off
	v_mfma_f32_32x32x16_bf16 v[32:47], v[96:99], v[84:87], v[32:47]
	v_mfma_f32_32x32x16_bf16 v[0:15], v[96:99], v[88:91], v[0:15]
	s_add_i32 m0, s98, 0x2000
	v_lshl_add_u64 v[254:255], v[72:73], 0, s[100:101]
	global_load_lds_dwordx4 v[254:255], off
	s_waitcnt lgkmcnt(0)
	v_add_u32_e32 v252, s12, v78
	v_add_u32_e32 v253, s12, v79
	ds_read_b128 v[84:87], v252
	ds_read_b128 v[88:91], v252 offset:4096
	ds_read_b128 v[92:95], v253 offset:16384
	ds_read_b128 v[96:99], v253 offset:20480
	v_mfma_f32_32x32x16_bf16 v[48:63], v[244:247], v[236:239], v[48:63]
	v_mfma_f32_32x32x16_bf16 v[16:31], v[244:247], v[240:243], v[16:31]
	s_add_i32 m0, s98, 0x4000
	v_lshl_add_u64 v[254:255], v[70:71], 0, s[100:101]
	global_load_lds_dwordx4 v[254:255], off
	v_mfma_f32_32x32x16_bf16 v[32:47], v[248:251], v[236:239], v[32:47]
	v_mfma_f32_32x32x16_bf16 v[0:15], v[248:251], v[240:243], v[0:15]
	s_add_i32 m0, s98, 0x6000
	v_lshl_add_u64 v[254:255], v[68:69], 0, s[100:101]
	global_load_lds_dwordx4 v[254:255], off
	s_waitcnt lgkmcnt(0)
	v_add_u32_e32 v252, s12, v76
	v_add_u32_e32 v253, s12, v77
	ds_read_b128 v[236:239], v252
	ds_read_b128 v[240:243], v252 offset:4096
	ds_read_b128 v[244:247], v253 offset:16384
	ds_read_b128 v[248:251], v253 offset:20480
	v_mfma_f32_32x32x16_bf16 v[48:63], v[92:95], v[84:87], v[48:63]
	v_mfma_f32_32x32x16_bf16 v[16:31], v[92:95], v[88:91], v[16:31]
	s_add_i32 m0, s98, 0x8000
	v_lshl_add_u64 v[254:255], v[66:67], 0, s[100:101]
	global_load_lds_dwordx4 v[254:255], off
	v_mfma_f32_32x32x16_bf16 v[32:47], v[96:99], v[84:87], v[32:47]
	v_mfma_f32_32x32x16_bf16 v[0:15], v[96:99], v[88:91], v[0:15]
	s_add_i32 m0, s98, 0xa000
	v_lshl_add_u64 v[254:255], v[64:65], 0, s[100:101]
	global_load_lds_dwordx4 v[254:255], off
	s_add_i32 s12, s3, 0xc000
	s_cmp_lg_u32 s3, 0x18000
	s_cselect_b32 s3, s12, 0
	s_waitcnt lgkmcnt(0)
	v_mfma_f32_32x32x16_bf16 v[48:63], v[244:247], v[236:239], v[48:63]
	s_add_i32 s12, s11, 0xc000
	s_cmp_lg_u32 s11, 0x18000
	s_waitcnt vmcnt(6) lgkmcnt(0)
	s_barrier
	s_cselect_b32 s11, s12, 0
	s_add_u32 s6, s6, 0x80
	v_mfma_f32_32x32x16_bf16 v[16:31], v[244:247], v[240:243], v[16:31]
	s_addc_u32 s7, s7, 0
	s_cmpk_lg_i32 s6, 0x700
	v_mfma_f32_32x32x16_bf16 v[32:47], v[248:251], v[236:239], v[32:47]
	v_mfma_f32_32x32x16_bf16 v[0:15], v[248:251], v[240:243], v[0:15]
	s_cbranch_scc1 .LBB0_280
; DEV int stage_next(int s) { return (s == 2 * GS_STAGE) ? 0 : s + GS_STAGE; }
; template <int WAIT0>
; DEV void gk_main(f32x16 (&acc)[2][2], const GTile& t, int s0) {
;     ...
;   GK_COMPUTE(stc);
;   vm_wait_bar<0>();
;   stc = stage_next(stc);
;   GK_COMPUTE(stc);
;   vm_wait_bar<0>();
	s_add_i32 s6, s3, 0
	v_add_u32_e32 v84, s6, v83
	ds_read_b128 v[64:67], v84 offset:16384
	v_add_u32_e32 v72, s6, v82
	ds_read_b128 v[68:71], v72
	ds_read_b128 v[72:75], v72 offset:4096
	s_waitcnt lgkmcnt(0)
	v_mfma_f32_32x32x16_bf16 v[48:63], v[64:67], v[68:71], v[48:63]
	v_mfma_f32_32x32x16_bf16 v[16:31], v[64:67], v[72:75], v[16:31]
	ds_read_b128 v[64:67], v84 offset:20480
	v_add_u32_e32 v84, s6, v81
	s_waitcnt lgkmcnt(0)
	v_mfma_f32_32x32x16_bf16 v[32:47], v[64:67], v[68:71], v[32:47]
	v_mfma_f32_32x32x16_bf16 v[0:15], v[64:67], v[72:75], v[0:15]
	ds_read_b128 v[64:67], v84 offset:16384
	v_add_u32_e32 v72, s6, v80
	ds_read_b128 v[68:71], v72
	ds_read_b128 v[72:75], v72 offset:4096
	s_waitcnt lgkmcnt(0)
	v_mfma_f32_32x32x16_bf16 v[48:63], v[64:67], v[68:71], v[48:63]
	v_mfma_f32_32x32x16_bf16 v[16:31], v[64:67], v[72:75], v[16:31]
	ds_read_b128 v[64:67], v84 offset:20480
	v_add_u32_e32 v84, s6, v79
	s_waitcnt lgkmcnt(0)
	v_mfma_f32_32x32x16_bf16 v[32:47], v[64:67], v[68:71], v[32:47]
	v_mfma_f32_32x32x16_bf16 v[0:15], v[64:67], v[72:75], v[0:15]
	ds_read_b128 v[64:67], v84 offset:16384
	v_add_u32_e32 v72, s6, v78
	ds_read_b128 v[68:71], v72
	ds_read_b128 v[72:75], v72 offset:4096
	s_waitcnt lgkmcnt(0)
	v_mfma_f32_32x32x16_bf16 v[48:63], v[64:67], v[68:71], v[48:63]
	v_mfma_f32_32x32x16_bf16 v[16:31], v[64:67], v[72:75], v[16:31]
	ds_read_b128 v[64:67], v84 offset:20480
	v_add_u32_e32 v84, s6, v77
	s_waitcnt lgkmcnt(0)
	v_mfma_f32_32x32x16_bf16 v[32:47], v[64:67], v[68:71], v[32:47]
	v_mfma_f32_32x32x16_bf16 v[0:15], v[64:67], v[72:75], v[0:15]
	ds_read_b128 v[64:67], v84 offset:16384
	v_add_u32_e32 v72, s6, v76
	ds_read_b128 v[68:71], v72
	ds_read_b128 v[72:75], v72 offset:4096
	s_add_i32 s6, s3, 0xc000
	s_cmp_lg_u32 s3, 0x18000
	s_cselect_b32 s3, s6, 0
	s_waitcnt lgkmcnt(0)
	v_mfma_f32_32x32x16_bf16 v[48:63], v[64:67], v[68:71], v[48:63]
	s_add_i32 s3, s3, 0
	v_add_u32_e32 v83, s3, v83
	v_add_u32_e32 v81, s3, v81
	v_add_u32_e32 v79, s3, v79
	v_add_u32_e32 v77, s3, v77
	v_mfma_f32_32x32x16_bf16 v[16:31], v[64:67], v[72:75], v[16:31]
	ds_read_b128 v[64:67], v84 offset:20480
	s_waitcnt vmcnt(0) lgkmcnt(0)
	s_barrier
	s_waitcnt lgkmcnt(0)
	v_mfma_f32_32x32x16_bf16 v[32:47], v[64:67], v[68:71], v[32:47]
	v_mfma_f32_32x32x16_bf16 v[0:15], v[64:67], v[72:75], v[0:15]
	ds_read_b128 v[64:67], v83 offset:16384
	v_add_u32_e32 v72, s3, v82
	ds_read_b128 v[68:71], v72
	ds_read_b128 v[72:75], v72 offset:4096
	s_waitcnt lgkmcnt(0)
	v_mfma_f32_32x32x16_bf16 v[48:63], v[64:67], v[68:71], v[48:63]
	v_mfma_f32_32x32x16_bf16 v[16:31], v[64:67], v[72:75], v[16:31]
	ds_read_b128 v[64:67], v83 offset:20480
	s_waitcnt lgkmcnt(0)
	v_mfma_f32_32x32x16_bf16 v[32:47], v[64:67], v[68:71], v[32:47]
	v_mfma_f32_32x32x16_bf16 v[0:15], v[64:67], v[72:75], v[0:15]
	ds_read_b128 v[64:67], v81 offset:16384
	v_add_u32_e32 v72, s3, v80
	ds_read_b128 v[68:71], v72
	ds_read_b128 v[72:75], v72 offset:4096
	s_waitcnt lgkmcnt(0)
	v_mfma_f32_32x32x16_bf16 v[48:63], v[64:67], v[68:71], v[48:63]
	v_mfma_f32_32x32x16_bf16 v[16:31], v[64:67], v[72:75], v[16:31]
	ds_read_b128 v[64:67], v81 offset:20480
	s_waitcnt lgkmcnt(0)
	v_mfma_f32_32x32x16_bf16 v[32:47], v[64:67], v[68:71], v[32:47]
	v_mfma_f32_32x32x16_bf16 v[0:15], v[64:67], v[72:75], v[0:15]
	ds_read_b128 v[64:67], v79 offset:16384
	v_add_u32_e32 v72, s3, v78
	ds_read_b128 v[68:71], v72
	ds_read_b128 v[72:75], v72 offset:4096
	s_waitcnt lgkmcnt(0)
	v_mfma_f32_32x32x16_bf16 v[48:63], v[64:67], v[68:71], v[48:63]
	v_mfma_f32_32x32x16_bf16 v[16:31], v[64:67], v[72:75], v[16:31]
	ds_read_b128 v[64:67], v79 offset:20480
	s_waitcnt lgkmcnt(0)
	v_mfma_f32_32x32x16_bf16 v[32:47], v[64:67], v[68:71], v[32:47]
	v_mfma_f32_32x32x16_bf16 v[0:15], v[64:67], v[72:75], v[0:15]
	ds_read_b128 v[64:67], v77 offset:16384
	v_add_u32_e32 v72, s3, v76
	ds_read_b128 v[68:71], v72
	ds_read_b128 v[72:75], v72 offset:4096
	s_waitcnt lgkmcnt(0)
	v_mfma_f32_32x32x16_bf16 v[48:63], v[64:67], v[68:71], v[48:63]
	v_mfma_f32_32x32x16_bf16 v[16:31], v[64:67], v[72:75], v[16:31]
	ds_read_b128 v[64:67], v77 offset:20480
	s_waitcnt vmcnt(0) lgkmcnt(0)
	s_barrier
	s_waitcnt lgkmcnt(0)
	v_mfma_f32_32x32x16_bf16 v[32:47], v[64:67], v[68:71], v[32:47]
	v_mfma_f32_32x32x16_bf16 v[0:15], v[64:67], v[72:75], v[0:15]

; DEV int stage_next(int s) { return (s == 2 * GS_STAGE) ? 0 : s + GS_STAGE; }
; template <int WAIT0>
; DEV void gk_main(f32x16 (&acc)[2][2], const GTile& t, int s0) {
;     ...
;   vm_wait_bar<WAIT0>();
;   int stc = s0, std_ = stage_next(stage_next(s0));
; #pragma nounroll
;   for (int kt = 0; kt < nk - 2; ++kt) {
;     GK_DMA(std_, kt + 2);
;     GK_COMPUTE(stc);
;     vm_wait_bar<6>();
;     stc = stage_next(stc); std_ = stage_next(std_);
;   }
.LBB0_286:
	s_add_i32 s12, s10, s11
	s_mov_b32 s98, s12
	s_mov_b64 s[100:101], s[6:7]
	s_add_i32 s12, s3, 0
	v_add_u32_e32 v252, s12, v82
	v_add_u32_e32 v253, s12, v83
	ds_read_b128 v[84:87], v252
	ds_read_b128 v[88:91], v252 offset:4096
	ds_read_b128 v[92:95], v253 offset:16384
	ds_read_b128 v[96:99], v253 offset:20480
	s_waitcnt lgkmcnt(0)
	v_add_u32_e32 v252, s12, v80
	v_add_u32_e32 v253, s12, v81
	ds_read_b128 v[236:239], v252
	ds_read_b128 v[240:243], v252 offset:4096
	ds_read_b128 v[244:247], v253 offset:16384
	ds_read_b128 v[248:251], v253 offset:20480
	v_mfma_f32_32x32x16_bf16 v[48:63], v[92:95], v[84:87], v[48:63]
	v_mfma_f32_32x32x16_bf16 v[16:31], v[92:95], v[88:91], v[16:31]
	s_mov_b32 m0, s98
	v_lshl_add_u64 v[254:255], v[74:75], 0, s[100:101]
	global_load_lds_dwordx4 v[254:255], off
	v_mfma_f32_32x32x16_bf16 v[32:47], v[96:99], v[84:87], v[32:47]
	v_mfma_f32_32x32x16_bf16 v[0:15], v[96:99], v[88:91], v[0:15]
	s_add_i32 m0, s98, 0x2000
	v_lshl_add_u64 v[254:255], v[72:73], 0, s[100:101]
	global_load_lds_dwordx4 v[254:255], off
	s_waitcnt lgkmcnt(0)
	v_add_u32_e32 v252, s12, v78
	v_add_u32_e32 v253, s12, v79
	ds_read_b128 v[84:87], v252
	ds_read_b128 v[88:91], v252 offset:4096
	ds_read_b128 v[92:95], v253 offset:16384
	ds_read_b128 v[96:99], v253 offset:20480
	v_mfma_f32_32x32x16_bf16 v[48:63], v[244:247], v[236:239], v[48:63]
	v_mfma_f32_32x32x16_bf16 v[16:31], v[244:247], v[240:243], v[16:31]
	s_add_i32 m0, s98, 0x4000
	v_lshl_add_u64 v[254:255], v[70:71], 0, s[100:101]
	global_load_lds_dwordx4 v[254:255], off
	v_mfma_f32_32x32x16_bf16 v[32:47], v[248:251], v[236:239], v[32:47]
	v_mfma_f32_32x32x16_bf16 v[0:15], v[248:251], v[240:243], v[0:15]
	s_add_i32 m0, s98, 0x6000
	v_lshl_add_u64 v[254:255], v[68:69], 0, s[100:101]
	global_load_lds_dwordx4 v[254:255], off
	s_waitcnt lgkmcnt(0)
	v_add_u32_e32 v252, s12, v76
	v_add_u32_e32 v253, s12, v77
	ds_read_b128 v[236:239], v252
	ds_read_b128 v[240:243], v252 offset:4096
	ds_read_b128 v[244:247], v253 offset:16384
	ds_read_b128 v[248:251], v253 offset:20480
	v_mfma_f32_32x32x16_bf16 v[48:63], v[92:95], v[84:87], v[48:63]
	v_mfma_f32_32x32x16_bf16 v[16:31], v[92:95], v[88:91], v[16:31]
	s_add_i32 m0, s98, 0x8000
	v_lshl_add_u64 v[254:255], v[66:67], 0, s[100:101]
	global_load_lds_dwordx4 v[254:255], off
	v_mfma_f32_32x32x16_bf16 v[32:47], v[96:99], v[84:87], v[32:47]
	v_mfma_f32_32x32x16_bf16 v[0:15], v[96:99], v[88:91], v[0:15]
	s_add_i32 m0, s98, 0xa000
	v_lshl_add_u64 v[254:255], v[64:65], 0, s[100:101]
	global_load_lds_dwordx4 v[254:255], off
	s_add_i32 s12, s3, 0xc000
	s_cmp_lg_u32 s3, 0x18000
	s_cselect_b32 s3, s12, 0
	s_waitcnt lgkmcnt(0)
	v_mfma_f32_32x32x16_bf16 v[48:63], v[244:247], v[236:239], v[48:63]
	s_add_i32 s12, s11, 0xc000
	s_cmp_lg_u32 s11, 0x18000
	s_waitcnt vmcnt(6) lgkmcnt(0)
	s_barrier
	s_cselect_b32 s11, s12, 0
	s_add_u32 s6, s6, 0x80
	v_mfma_f32_32x32x16_bf16 v[16:31], v[244:247], v[240:243], v[16:31]
	s_addc_u32 s7, s7, 0
	s_cmpk_lg_i32 s6, 0x700
	v_mfma_f32_32x32x16_bf16 v[32:47], v[248:251], v[236:239], v[32:47]
	v_mfma_f32_32x32x16_bf16 v[0:15], v[248:251], v[240:243], v[0:15]
	s_cbranch_scc1 .LBB0_286
; DEV int stage_next(int s) { return (s == 2 * GS_STAGE) ? 0 : s + GS_STAGE; }
; template <int WAIT0>
; DEV void gk_main(f32x16 (&acc)[2][2], const GTile& t, int s0) {
;     ...
;   GK_COMPUTE(stc);
;   vm_wait_bar<0>();
;   stc = stage_next(stc);
;   GK_COMPUTE(stc);
;   vm_wait_bar<0>();
	s_add_i32 s6, s3, 0
	v_add_u32_e32 v84, s6, v83
	ds_read_b128 v[64:67], v84 offset:16384
	v_add_u32_e32 v72, s6, v82
	ds_read_b128 v[68:71], v72
	ds_read_b128 v[72:75], v72 offset:4096
	s_waitcnt lgkmcnt(0)
	v_mfma_f32_32x32x16_bf16 v[48:63], v[64:67], v[68:71], v[48:63]
	v_mfma_f32_32x32x16_bf16 v[16:31], v[64:67], v[72:75], v[16:31]
	ds_read_b128 v[64:67], v84 offset:20480
	v_add_u32_e32 v84, s6, v81
	s_waitcnt lgkmcnt(0)
	v_mfma_f32_32x32x16_bf16 v[32:47], v[64:67], v[68:71], v[32:47]
	v_mfma_f32_32x32x16_bf16 v[0:15], v[64:67], v[72:75], v[0:15]
	ds_read_b128 v[64:67], v84 offset:16384
	v_add_u32_e32 v72, s6, v80
	ds_read_b128 v[68:71], v72
	ds_read_b128 v[72:75], v72 offset:4096
	s_waitcnt lgkmcnt(0)
	v_mfma_f32_32x32x16_bf16 v[48:63], v[64:67], v[68:71], v[48:63]
	v_mfma_f32_32x32x16_bf16 v[16:31], v[64:67], v[72:75], v[16:31]
	ds_read_b128 v[64:67], v84 offset:20480
	v_add_u32_e32 v84, s6, v79
	s_waitcnt lgkmcnt(0)
	v_mfma_f32_32x32x16_bf16 v[32:47], v[64:67], v[68:71], v[32:47]
	v_mfma_f32_32x32x16_bf16 v[0:15], v[64:67], v[72:75], v[0:15]
	ds_read_b128 v[64:67], v84 offset:16384
	v_add_u32_e32 v72, s6, v78
	ds_read_b128 v[68:71], v72
	ds_read_b128 v[72:75], v72 offset:4096
	s_waitcnt lgkmcnt(0)
	v_mfma_f32_32x32x16_bf16 v[48:63], v[64:67], v[68:71], v[48:63]
	v_mfma_f32_32x32x16_bf16 v[16:31], v[64:67], v[72:75], v[16:31]
	ds_read_b128 v[64:67], v84 offset:20480
	v_add_u32_e32 v84, s6, v77
	s_waitcnt lgkmcnt(0)
	v_mfma_f32_32x32x16_bf16 v[32:47], v[64:67], v[68:71], v[32:47]
	v_mfma_f32_32x32x16_bf16 v[0:15], v[64:67], v[72:75], v[0:15]
	ds_read_b128 v[64:67], v84 offset:16384
	v_add_u32_e32 v72, s6, v76
	ds_read_b128 v[68:71], v72
	ds_read_b128 v[72:75], v72 offset:4096
	s_add_i32 s6, s3, 0xc000
	s_cmp_lg_u32 s3, 0x18000
	s_cselect_b32 s3, s6, 0
	s_waitcnt lgkmcnt(0)
	v_mfma_f32_32x32x16_bf16 v[48:63], v[64:67], v[68:71], v[48:63]
	s_add_i32 s3, s3, 0
	v_add_u32_e32 v83, s3, v83
	v_add_u32_e32 v81, s3, v81
	v_add_u32_e32 v79, s3, v79
	v_add_u32_e32 v77, s3, v77
	v_mfma_f32_32x32x16_bf16 v[16:31], v[64:67], v[72:75], v[16:31]
	ds_read_b128 v[64:67], v84 offset:20480
	s_waitcnt vmcnt(0) lgkmcnt(0)
	s_barrier
	s_waitcnt lgkmcnt(0)
	v_mfma_f32_32x32x16_bf16 v[32:47], v[64:67], v[68:71], v[32:47]
	v_mfma_f32_32x32x16_bf16 v[0:15], v[64:67], v[72:75], v[0:15]
	ds_read_b128 v[64:67], v83 offset:16384
	v_add_u32_e32 v72, s3, v82
	ds_read_b128 v[68:71], v72
	ds_read_b128 v[72:75], v72 offset:4096
	s_waitcnt lgkmcnt(0)
	v_mfma_f32_32x32x16_bf16 v[48:63], v[64:67], v[68:71], v[48:63]
	v_mfma_f32_32x32x16_bf16 v[16:31], v[64:67], v[72:75], v[16:31]
	ds_read_b128 v[64:67], v83 offset:20480
	s_waitcnt lgkmcnt(0)
	v_mfma_f32_32x32x16_bf16 v[32:47], v[64:67], v[68:71], v[32:47]
	v_mfma_f32_32x32x16_bf16 v[0:15], v[64:67], v[72:75], v[0:15]
	ds_read_b128 v[64:67], v81 offset:16384
	v_add_u32_e32 v72, s3, v80
	ds_read_b128 v[68:71], v72
	ds_read_b128 v[72:75], v72 offset:4096
	s_waitcnt lgkmcnt(0)
	v_mfma_f32_32x32x16_bf16 v[48:63], v[64:67], v[68:71], v[48:63]
	v_mfma_f32_32x32x16_bf16 v[16:31], v[64:67], v[72:75], v[16:31]
	ds_read_b128 v[64:67], v81 offset:20480
	s_waitcnt lgkmcnt(0)
	v_mfma_f32_32x32x16_bf16 v[32:47], v[64:67], v[68:71], v[32:47]
	v_mfma_f32_32x32x16_bf16 v[0:15], v[64:67], v[72:75], v[0:15]
	ds_read_b128 v[64:67], v79 offset:16384
	v_add_u32_e32 v72, s3, v78
	ds_read_b128 v[68:71], v72
	ds_read_b128 v[72:75], v72 offset:4096
	s_waitcnt lgkmcnt(0)
	v_mfma_f32_32x32x16_bf16 v[48:63], v[64:67], v[68:71], v[48:63]
	v_mfma_f32_32x32x16_bf16 v[16:31], v[64:67], v[72:75], v[16:31]
	ds_read_b128 v[64:67], v79 offset:20480
	s_waitcnt lgkmcnt(0)
	v_mfma_f32_32x32x16_bf16 v[32:47], v[64:67], v[68:71], v[32:47]
	v_mfma_f32_32x32x16_bf16 v[0:15], v[64:67], v[72:75], v[0:15]
	ds_read_b128 v[64:67], v77 offset:16384
	v_add_u32_e32 v72, s3, v76
	ds_read_b128 v[68:71], v72
	ds_read_b128 v[72:75], v72 offset:4096
	s_waitcnt lgkmcnt(0)
	v_mfma_f32_32x32x16_bf16 v[48:63], v[64:67], v[68:71], v[48:63]
	v_mfma_f32_32x32x16_bf16 v[16:31], v[64:67], v[72:75], v[16:31]
	ds_read_b128 v[64:67], v77 offset:20480
	s_waitcnt vmcnt(0) lgkmcnt(0)
	s_barrier
	s_waitcnt lgkmcnt(0)
	v_mfma_f32_32x32x16_bf16 v[32:47], v[64:67], v[68:71], v[32:47]
	v_mfma_f32_32x32x16_bf16 v[0:15], v[64:67], v[72:75], v[0:15]
	s_add_i32 s3, s2, 1
	s_cmp_eq_u32 s2, 3
	s_cbranch_scc1 .LBB0_272

; DEV int stage_next(int s) { return (s == 2 * GS_STAGE) ? 0 : s + GS_STAGE; }
; template <int WAIT0>
; DEV void gk_main(f32x16 (&acc)[2][2], const GTile& t, int s0) {
;     ...
;   vm_wait_bar<WAIT0>();
;   int stc = s0, std_ = stage_next(stage_next(s0));
; #pragma nounroll
;   for (int kt = 0; kt < nk - 2; ++kt) {
;     GK_DMA(std_, kt + 2);
;     GK_COMPUTE(stc);
;     vm_wait_bar<6>();
;     stc = stage_next(stc); std_ = stage_next(std_);
;   }
.LBB0_298:
	s_add_i32 s16, s1, s3
	s_mov_b32 s98, s16
	s_mov_b64 s[100:101], s[10:11]
	s_add_i32 s16, s0, 0
	v_add_u32_e32 v87, s16, v85
	ds_read_b128 v[88:91], v87
	ds_read_b128 v[92:95], v87 offset:4096
	v_add_u32_e32 v87, s16, v86
	ds_read_b128 v[96:99], v87 offset:16384
	ds_read_b128 v[100:103], v87 offset:20480
	s_waitcnt lgkmcnt(0)
	v_add_u32_e32 v87, s16, v83
	ds_read_b128 v[236:239], v87
	ds_read_b128 v[240:243], v87 offset:4096
	v_add_u32_e32 v87, s16, v84
	ds_read_b128 v[244:247], v87 offset:16384
	ds_read_b128 v[248:251], v87 offset:20480
	v_mfma_f32_32x32x16_bf16 v[48:63], v[96:99], v[88:91], v[48:63]
	v_mfma_f32_32x32x16_bf16 v[32:47], v[96:99], v[92:95], v[32:47]
	s_mov_b32 m0, s98
	v_lshl_add_u64 v[254:255], v[76:77], 0, s[100:101]
	global_load_lds_dwordx4 v[254:255], off
	v_mfma_f32_32x32x16_bf16 v[16:31], v[100:103], v[88:91], v[16:31]
	v_mfma_f32_32x32x16_bf16 v[0:15], v[100:103], v[92:95], v[0:15]
	s_add_i32 m0, s98, 0x2000
	v_lshl_add_u64 v[254:255], v[74:75], 0, s[100:101]
	global_load_lds_dwordx4 v[254:255], off
	v_add_u32_e32 v87, s16, v81
	s_waitcnt lgkmcnt(0)
	ds_read_b128 v[88:91], v87
	ds_read_b128 v[92:95], v87 offset:4096
	v_add_u32_e32 v87, s16, v82
	ds_read_b128 v[96:99], v87 offset:16384
	ds_read_b128 v[100:103], v87 offset:20480
	v_mfma_f32_32x32x16_bf16 v[48:63], v[244:247], v[236:239], v[48:63]
	v_mfma_f32_32x32x16_bf16 v[32:47], v[244:247], v[240:243], v[32:47]
	s_add_i32 m0, s98, 0x4000
	v_lshl_add_u64 v[254:255], v[72:73], 0, s[100:101]
	global_load_lds_dwordx4 v[254:255], off
	v_mfma_f32_32x32x16_bf16 v[16:31], v[248:251], v[236:239], v[16:31]
	v_mfma_f32_32x32x16_bf16 v[0:15], v[248:251], v[240:243], v[0:15]
	s_add_i32 m0, s98, 0x6000
	v_lshl_add_u64 v[254:255], v[70:71], 0, s[100:101]
	global_load_lds_dwordx4 v[254:255], off
	v_add_u32_e32 v87, s16, v79
	s_waitcnt lgkmcnt(0)
	ds_read_b128 v[236:239], v87
	ds_read_b128 v[240:243], v87 offset:4096
	v_add_u32_e32 v87, s16, v80
	ds_read_b128 v[244:247], v87 offset:16384
	ds_read_b128 v[248:251], v87 offset:20480
	v_mfma_f32_32x32x16_bf16 v[48:63], v[96:99], v[88:91], v[48:63]
	v_mfma_f32_32x32x16_bf16 v[32:47], v[96:99], v[92:95], v[32:47]
	s_add_i32 m0, s98, 0x8000
	v_lshl_add_u64 v[254:255], v[68:69], 0, s[100:101]
	global_load_lds_dwordx4 v[254:255], off
	v_mfma_f32_32x32x16_bf16 v[16:31], v[100:103], v[88:91], v[16:31]
	v_mfma_f32_32x32x16_bf16 v[0:15], v[100:103], v[92:95], v[0:15]
	s_add_i32 m0, s98, 0xa000
	v_lshl_add_u64 v[254:255], v[66:67], 0, s[100:101]
	global_load_lds_dwordx4 v[254:255], off
	s_add_i32 s16, s0, 0xc000
	s_cmp_lg_u32 s0, 0x18000
	s_cselect_b32 s0, s16, 0
	s_add_i32 s16, s3, 0xc000
	s_waitcnt lgkmcnt(0)
	v_mfma_f32_32x32x16_bf16 v[48:63], v[244:247], v[236:239], v[48:63]
	s_cmp_lg_u32 s3, 0x18000
	s_waitcnt vmcnt(6) lgkmcnt(0)
	s_barrier
	s_cselect_b32 s3, s16, 0
	s_add_u32 s10, s10, 0x80
	s_addc_u32 s11, s11, 0
	v_mfma_f32_32x32x16_bf16 v[32:47], v[244:247], v[240:243], v[32:47]
	s_cmpk_lg_i32 s10, 0x700
	v_mfma_f32_32x32x16_bf16 v[16:31], v[248:251], v[236:239], v[16:31]
	v_mfma_f32_32x32x16_bf16 v[0:15], v[248:251], v[240:243], v[0:15]
	s_cbranch_scc1 .LBB0_298
; DEV int stage_next(int s) { return (s == 2 * GS_STAGE) ? 0 : s + GS_STAGE; }
; template <int WAIT0>
; DEV void gk_main(f32x16 (&acc)[2][2], const GTile& t, int s0) {
;     ...
;   GK_COMPUTE(stc);
;   vm_wait_bar<0>();
;   stc = stage_next(stc);
;   GK_COMPUTE(stc);
;   vm_wait_bar<0>();
	s_add_i32 s1, s0, 0
	v_add_u32_e32 v87, s1, v86
	ds_read_b128 v[66:69], v87 offset:16384
	v_add_u32_e32 v74, s1, v85
	ds_read_b128 v[70:73], v74
	ds_read_b128 v[74:77], v74 offset:4096
	s_waitcnt lgkmcnt(0)
	v_mfma_f32_32x32x16_bf16 v[48:63], v[66:69], v[70:73], v[48:63]
	v_mfma_f32_32x32x16_bf16 v[32:47], v[66:69], v[74:77], v[32:47]
	ds_read_b128 v[66:69], v87 offset:20480
	v_add_u32_e32 v87, s1, v84
	s_waitcnt lgkmcnt(0)
	v_mfma_f32_32x32x16_bf16 v[16:31], v[66:69], v[70:73], v[16:31]
	v_mfma_f32_32x32x16_bf16 v[0:15], v[66:69], v[74:77], v[0:15]
	ds_read_b128 v[66:69], v87 offset:16384
	v_add_u32_e32 v74, s1, v83
	ds_read_b128 v[70:73], v74
	ds_read_b128 v[74:77], v74 offset:4096
	s_waitcnt lgkmcnt(0)
	v_mfma_f32_32x32x16_bf16 v[48:63], v[66:69], v[70:73], v[48:63]
	v_mfma_f32_32x32x16_bf16 v[32:47], v[66:69], v[74:77], v[32:47]
	ds_read_b128 v[66:69], v87 offset:20480
	v_add_u32_e32 v87, s1, v82
	s_waitcnt lgkmcnt(0)
	v_mfma_f32_32x32x16_bf16 v[16:31], v[66:69], v[70:73], v[16:31]
	v_mfma_f32_32x32x16_bf16 v[0:15], v[66:69], v[74:77], v[0:15]
	ds_read_b128 v[66:69], v87 offset:16384
	v_add_u32_e32 v74, s1, v81
	ds_read_b128 v[70:73], v74
	ds_read_b128 v[74:77], v74 offset:4096
	s_waitcnt lgkmcnt(0)
	v_mfma_f32_32x32x16_bf16 v[48:63], v[66:69], v[70:73], v[48:63]
	v_mfma_f32_32x32x16_bf16 v[32:47], v[66:69], v[74:77], v[32:47]
	ds_read_b128 v[66:69], v87 offset:20480
	v_add_u32_e32 v87, s1, v80
	s_waitcnt lgkmcnt(0)
	v_mfma_f32_32x32x16_bf16 v[16:31], v[66:69], v[70:73], v[16:31]
	v_mfma_f32_32x32x16_bf16 v[0:15], v[66:69], v[74:77], v[0:15]
	ds_read_b128 v[66:69], v87 offset:16384
	v_add_u32_e32 v74, s1, v79
	ds_read_b128 v[70:73], v74
	ds_read_b128 v[74:77], v74 offset:4096
	s_add_i32 s1, s0, 0xc000
	s_cmp_lg_u32 s0, 0x18000
	s_cselect_b32 s0, s1, 0
	s_waitcnt lgkmcnt(0)
	v_mfma_f32_32x32x16_bf16 v[48:63], v[66:69], v[70:73], v[48:63]
	s_add_i32 s0, s0, 0
	v_add_u32_e32 v86, s0, v86
	v_add_u32_e32 v84, s0, v84
	v_add_u32_e32 v82, s0, v82
	v_add_u32_e32 v80, s0, v80
	v_mfma_f32_32x32x16_bf16 v[32:47], v[66:69], v[74:77], v[32:47]
	ds_read_b128 v[66:69], v87 offset:20480
	s_waitcnt vmcnt(0) lgkmcnt(0)
	s_barrier
	s_waitcnt lgkmcnt(0)
	v_mfma_f32_32x32x16_bf16 v[16:31], v[66:69], v[70:73], v[16:31]
	v_mfma_f32_32x32x16_bf16 v[0:15], v[66:69], v[74:77], v[0:15]
	ds_read_b128 v[66:69], v86 offset:16384
	v_add_u32_e32 v74, s0, v85
	ds_read_b128 v[70:73], v74
	ds_read_b128 v[74:77], v74 offset:4096
	s_waitcnt lgkmcnt(0)
	v_mfma_f32_32x32x16_bf16 v[48:63], v[66:69], v[70:73], v[48:63]
	v_mfma_f32_32x32x16_bf16 v[32:47], v[66:69], v[74:77], v[32:47]
	ds_read_b128 v[66:69], v86 offset:20480
	s_waitcnt lgkmcnt(0)
	v_mfma_f32_32x32x16_bf16 v[16:31], v[66:69], v[70:73], v[16:31]
	v_mfma_f32_32x32x16_bf16 v[0:15], v[66:69], v[74:77], v[0:15]
	ds_read_b128 v[66:69], v84 offset:16384
	v_add_u32_e32 v74, s0, v83
	ds_read_b128 v[70:73], v74
	ds_read_b128 v[74:77], v74 offset:4096
	s_waitcnt lgkmcnt(0)
	v_mfma_f32_32x32x16_bf16 v[48:63], v[66:69], v[70:73], v[48:63]
	v_mfma_f32_32x32x16_bf16 v[32:47], v[66:69], v[74:77], v[32:47]
	ds_read_b128 v[66:69], v84 offset:20480
	s_waitcnt lgkmcnt(0)
	v_mfma_f32_32x32x16_bf16 v[16:31], v[66:69], v[70:73], v[16:31]
	v_mfma_f32_32x32x16_bf16 v[0:15], v[66:69], v[74:77], v[0:15]
	ds_read_b128 v[66:69], v82 offset:16384
	v_add_u32_e32 v74, s0, v81
	ds_read_b128 v[70:73], v74
	ds_read_b128 v[74:77], v74 offset:4096
	s_waitcnt lgkmcnt(0)
	v_mfma_f32_32x32x16_bf16 v[48:63], v[66:69], v[70:73], v[48:63]
	v_mfma_f32_32x32x16_bf16 v[32:47], v[66:69], v[74:77], v[32:47]
	ds_read_b128 v[66:69], v82 offset:20480
	s_waitcnt lgkmcnt(0)
	v_mfma_f32_32x32x16_bf16 v[16:31], v[66:69], v[70:73], v[16:31]
	v_mfma_f32_32x32x16_bf16 v[0:15], v[66:69], v[74:77], v[0:15]
	ds_read_b128 v[66:69], v80 offset:16384
	v_add_u32_e32 v74, s0, v79
	ds_read_b128 v[70:73], v74
	ds_read_b128 v[74:77], v74 offset:4096
	s_mov_b64 s[0:1], 0
	s_waitcnt lgkmcnt(0)
	v_mfma_f32_32x32x16_bf16 v[48:63], v[66:69], v[70:73], v[48:63]
	v_mfma_f32_32x32x16_bf16 v[32:47], v[66:69], v[74:77], v[32:47]
	ds_read_b128 v[66:69], v80 offset:20480
	s_waitcnt vmcnt(0) lgkmcnt(0)
	s_barrier
	s_waitcnt lgkmcnt(0)
	v_mfma_f32_32x32x16_bf16 v[16:31], v[66:69], v[70:73], v[16:31]
	v_mfma_f32_32x32x16_bf16 v[0:15], v[66:69], v[74:77], v[0:15]

; DEV int stage_next(int s) { return (s == 2 * GS_STAGE) ? 0 : s + GS_STAGE; }
; template <int WAIT0>
; DEV void gk_main(f32x16 (&acc)[2][2], const GTile& t, int s0) {
;     ...
;   vm_wait_bar<WAIT0>();
;   int stc = s0, std_ = stage_next(stage_next(s0));
; #pragma nounroll
;   for (int kt = 0; kt < nk - 2; ++kt) {
;     GK_DMA(std_, kt + 2);
;     GK_COMPUTE(stc);
;     vm_wait_bar<6>();
;     stc = stage_next(stc); std_ = stage_next(std_);
;   }
.LBB0_302:
	s_add_i32 s16, s1, s3
	s_mov_b32 s98, s16
	s_mov_b64 s[100:101], s[10:11]
	s_add_i32 s16, s0, 0
	v_add_u32_e32 v87, s16, v85
	ds_read_b128 v[88:91], v87
	ds_read_b128 v[92:95], v87 offset:4096
	v_add_u32_e32 v87, s16, v86
	ds_read_b128 v[96:99], v87 offset:16384
	ds_read_b128 v[100:103], v87 offset:20480
	s_waitcnt lgkmcnt(0)
	v_add_u32_e32 v87, s16, v83
	ds_read_b128 v[236:239], v87
	ds_read_b128 v[240:243], v87 offset:4096
	v_add_u32_e32 v87, s16, v84
	ds_read_b128 v[244:247], v87 offset:16384
	ds_read_b128 v[248:251], v87 offset:20480
	v_mfma_f32_32x32x16_bf16 v[48:63], v[96:99], v[88:91], v[48:63]
	v_mfma_f32_32x32x16_bf16 v[32:47], v[96:99], v[92:95], v[32:47]
	s_mov_b32 m0, s98
	v_lshl_add_u64 v[254:255], v[76:77], 0, s[100:101]
	global_load_lds_dwordx4 v[254:255], off
	v_mfma_f32_32x32x16_bf16 v[16:31], v[100:103], v[88:91], v[16:31]
	v_mfma_f32_32x32x16_bf16 v[0:15], v[100:103], v[92:95], v[0:15]
	s_add_i32 m0, s98, 0x2000
	v_lshl_add_u64 v[254:255], v[74:75], 0, s[100:101]
	global_load_lds_dwordx4 v[254:255], off
	v_add_u32_e32 v87, s16, v81
	s_waitcnt lgkmcnt(0)
	ds_read_b128 v[88:91], v87
	ds_read_b128 v[92:95], v87 offset:4096
	v_add_u32_e32 v87, s16, v82
	ds_read_b128 v[96:99], v87 offset:16384
	ds_read_b128 v[100:103], v87 offset:20480
	v_mfma_f32_32x32x16_bf16 v[48:63], v[244:247], v[236:239], v[48:63]
	v_mfma_f32_32x32x16_bf16 v[32:47], v[244:247], v[240:243], v[32:47]
	s_add_i32 m0, s98, 0x4000
	v_lshl_add_u64 v[254:255], v[72:73], 0, s[100:101]
	global_load_lds_dwordx4 v[254:255], off
	v_mfma_f32_32x32x16_bf16 v[16:31], v[248:251], v[236:239], v[16:31]
	v_mfma_f32_32x32x16_bf16 v[0:15], v[248:251], v[240:243], v[0:15]
	s_add_i32 m0, s98, 0x6000
	v_lshl_add_u64 v[254:255], v[70:71], 0, s[100:101]
	global_load_lds_dwordx4 v[254:255], off
	v_add_u32_e32 v87, s16, v79
	s_waitcnt lgkmcnt(0)
	ds_read_b128 v[236:239], v87
	ds_read_b128 v[240:243], v87 offset:4096
	v_add_u32_e32 v87, s16, v80
	ds_read_b128 v[244:247], v87 offset:16384
	ds_read_b128 v[248:251], v87 offset:20480
	v_mfma_f32_32x32x16_bf16 v[48:63], v[96:99], v[88:91], v[48:63]
	v_mfma_f32_32x32x16_bf16 v[32:47], v[96:99], v[92:95], v[32:47]
	s_add_i32 m0, s98, 0x8000
	v_lshl_add_u64 v[254:255], v[68:69], 0, s[100:101]
	global_load_lds_dwordx4 v[254:255], off
	v_mfma_f32_32x32x16_bf16 v[16:31], v[100:103], v[88:91], v[16:31]
	v_mfma_f32_32x32x16_bf16 v[0:15], v[100:103], v[92:95], v[0:15]
	s_add_i32 m0, s98, 0xa000
	v_lshl_add_u64 v[254:255], v[66:67], 0, s[100:101]
	global_load_lds_dwordx4 v[254:255], off
	s_add_i32 s16, s0, 0xc000
	s_cmp_lg_u32 s0, 0x18000
	s_cselect_b32 s0, s16, 0
	s_add_i32 s16, s3, 0xc000
	s_waitcnt lgkmcnt(0)
	v_mfma_f32_32x32x16_bf16 v[48:63], v[244:247], v[236:239], v[48:63]
	s_cmp_lg_u32 s3, 0x18000
	s_waitcnt vmcnt(6) lgkmcnt(0)
	s_barrier
	s_cselect_b32 s3, s16, 0
	s_add_u32 s10, s10, 0x80
	s_addc_u32 s11, s11, 0
	v_mfma_f32_32x32x16_bf16 v[32:47], v[244:247], v[240:243], v[32:47]
	s_cmpk_lg_i32 s10, 0x700
	v_mfma_f32_32x32x16_bf16 v[16:31], v[248:251], v[236:239], v[16:31]
	v_mfma_f32_32x32x16_bf16 v[0:15], v[248:251], v[240:243], v[0:15]
	s_cbranch_scc1 .LBB0_302
; DEV int stage_next(int s) { return (s == 2 * GS_STAGE) ? 0 : s + GS_STAGE; }
; template <int WAIT0>
; DEV void gk_main(f32x16 (&acc)[2][2], const GTile& t, int s0) {
;     ...
;   GK_COMPUTE(stc);
;   vm_wait_bar<0>();
;   stc = stage_next(stc);
;   GK_COMPUTE(stc);
;   vm_wait_bar<0>();
	s_add_i32 s1, s0, 0
	v_add_u32_e32 v87, s1, v86
	ds_read_b128 v[66:69], v87 offset:16384
	v_add_u32_e32 v74, s1, v85
	ds_read_b128 v[70:73], v74
	ds_read_b128 v[74:77], v74 offset:4096
	s_waitcnt lgkmcnt(0)
	v_mfma_f32_32x32x16_bf16 v[48:63], v[66:69], v[70:73], v[48:63]
	v_mfma_f32_32x32x16_bf16 v[32:47], v[66:69], v[74:77], v[32:47]
	ds_read_b128 v[66:69], v87 offset:20480
	v_add_u32_e32 v87, s1, v84
	s_waitcnt lgkmcnt(0)
	v_mfma_f32_32x32x16_bf16 v[16:31], v[66:69], v[70:73], v[16:31]
	v_mfma_f32_32x32x16_bf16 v[0:15], v[66:69], v[74:77], v[0:15]
	ds_read_b128 v[66:69], v87 offset:16384
	v_add_u32_e32 v74, s1, v83
	ds_read_b128 v[70:73], v74
	ds_read_b128 v[74:77], v74 offset:4096
	s_waitcnt lgkmcnt(0)
	v_mfma_f32_32x32x16_bf16 v[48:63], v[66:69], v[70:73], v[48:63]
	v_mfma_f32_32x32x16_bf16 v[32:47], v[66:69], v[74:77], v[32:47]
	ds_read_b128 v[66:69], v87 offset:20480
	v_add_u32_e32 v87, s1, v82
	s_waitcnt lgkmcnt(0)
	v_mfma_f32_32x32x16_bf16 v[16:31], v[66:69], v[70:73], v[16:31]
	v_mfma_f32_32x32x16_bf16 v[0:15], v[66:69], v[74:77], v[0:15]
	ds_read_b128 v[66:69], v87 offset:16384
	v_add_u32_e32 v74, s1, v81
	ds_read_b128 v[70:73], v74
	ds_read_b128 v[74:77], v74 offset:4096
	s_waitcnt lgkmcnt(0)
	v_mfma_f32_32x32x16_bf16 v[48:63], v[66:69], v[70:73], v[48:63]
	v_mfma_f32_32x32x16_bf16 v[32:47], v[66:69], v[74:77], v[32:47]
	ds_read_b128 v[66:69], v87 offset:20480
	v_add_u32_e32 v87, s1, v80
	s_waitcnt lgkmcnt(0)
	v_mfma_f32_32x32x16_bf16 v[16:31], v[66:69], v[70:73], v[16:31]
	v_mfma_f32_32x32x16_bf16 v[0:15], v[66:69], v[74:77], v[0:15]
	ds_read_b128 v[66:69], v87 offset:16384
	v_add_u32_e32 v74, s1, v79
	ds_read_b128 v[70:73], v74
	ds_read_b128 v[74:77], v74 offset:4096
	s_add_i32 s1, s0, 0xc000
	s_cmp_lg_u32 s0, 0x18000
	s_cselect_b32 s0, s1, 0
	s_waitcnt lgkmcnt(0)
	v_mfma_f32_32x32x16_bf16 v[48:63], v[66:69], v[70:73], v[48:63]
	s_add_i32 s0, s0, 0
	v_add_u32_e32 v86, s0, v86
	v_add_u32_e32 v84, s0, v84
	v_add_u32_e32 v82, s0, v82
	v_add_u32_e32 v80, s0, v80
	v_mfma_f32_32x32x16_bf16 v[32:47], v[66:69], v[74:77], v[32:47]
	ds_read_b128 v[66:69], v87 offset:20480
	s_waitcnt vmcnt(0) lgkmcnt(0)
	s_barrier
	s_waitcnt lgkmcnt(0)
	v_mfma_f32_32x32x16_bf16 v[16:31], v[66:69], v[70:73], v[16:31]
	v_mfma_f32_32x32x16_bf16 v[0:15], v[66:69], v[74:77], v[0:15]
	ds_read_b128 v[66:69], v86 offset:16384
	v_add_u32_e32 v74, s0, v85
	ds_read_b128 v[70:73], v74
	ds_read_b128 v[74:77], v74 offset:4096
	s_waitcnt lgkmcnt(0)
	v_mfma_f32_32x32x16_bf16 v[48:63], v[66:69], v[70:73], v[48:63]
	v_mfma_f32_32x32x16_bf16 v[32:47], v[66:69], v[74:77], v[32:47]
	ds_read_b128 v[66:69], v86 offset:20480
	s_waitcnt lgkmcnt(0)
	v_mfma_f32_32x32x16_bf16 v[16:31], v[66:69], v[70:73], v[16:31]
	v_mfma_f32_32x32x16_bf16 v[0:15], v[66:69], v[74:77], v[0:15]
	ds_read_b128 v[66:69], v84 offset:16384
	v_add_u32_e32 v74, s0, v83
	ds_read_b128 v[70:73], v74
	ds_read_b128 v[74:77], v74 offset:4096
	s_waitcnt lgkmcnt(0)
	v_mfma_f32_32x32x16_bf16 v[48:63], v[66:69], v[70:73], v[48:63]
	v_mfma_f32_32x32x16_bf16 v[32:47], v[66:69], v[74:77], v[32:47]
	ds_read_b128 v[66:69], v84 offset:20480
	s_waitcnt lgkmcnt(0)
	v_mfma_f32_32x32x16_bf16 v[16:31], v[66:69], v[70:73], v[16:31]
	v_mfma_f32_32x32x16_bf16 v[0:15], v[66:69], v[74:77], v[0:15]
	ds_read_b128 v[66:69], v82 offset:16384
	v_add_u32_e32 v74, s0, v81
	ds_read_b128 v[70:73], v74
	ds_read_b128 v[74:77], v74 offset:4096
	s_waitcnt lgkmcnt(0)
	v_mfma_f32_32x32x16_bf16 v[48:63], v[66:69], v[70:73], v[48:63]
	v_mfma_f32_32x32x16_bf16 v[32:47], v[66:69], v[74:77], v[32:47]
	ds_read_b128 v[66:69], v82 offset:20480
	s_waitcnt lgkmcnt(0)
	v_mfma_f32_32x32x16_bf16 v[16:31], v[66:69], v[70:73], v[16:31]
	v_mfma_f32_32x32x16_bf16 v[0:15], v[66:69], v[74:77], v[0:15]
	ds_read_b128 v[66:69], v80 offset:16384
	v_add_u32_e32 v74, s0, v79
	ds_read_b128 v[70:73], v74
	ds_read_b128 v[74:77], v74 offset:4096
	s_waitcnt lgkmcnt(0)
	v_mfma_f32_32x32x16_bf16 v[48:63], v[66:69], v[70:73], v[48:63]
	v_mfma_f32_32x32x16_bf16 v[32:47], v[66:69], v[74:77], v[32:47]
	ds_read_b128 v[66:69], v80 offset:20480
	s_waitcnt vmcnt(0) lgkmcnt(0)
	s_barrier
	s_waitcnt lgkmcnt(0)
	v_mfma_f32_32x32x16_bf16 v[16:31], v[66:69], v[70:73], v[16:31]
	v_mfma_f32_32x32x16_bf16 v[0:15], v[66:69], v[74:77], v[0:15]

; DEV int stage_next(int s) { return (s == 2 * GS_STAGE) ? 0 : s + GS_STAGE; }
; template <int WAIT0>
; DEV void gk_main(f32x16 (&acc)[2][2], const GTile& t, int s0) {
;     ...
;   vm_wait_bar<WAIT0>();
;   int stc = s0, std_ = stage_next(stage_next(s0));
; #pragma nounroll
;   for (int kt = 0; kt < nk - 2; ++kt) {
;     GK_DMA(std_, kt + 2);
;     GK_COMPUTE(stc);
;     vm_wait_bar<6>();
;     stc = stage_next(stc); std_ = stage_next(std_);
;   }
.LBB0_308:
	s_add_i32 s3, s0, s1
	s_mov_b32 s98, s3
	s_mov_b64 s[100:101], s[10:11]
	s_add_i32 s3, s14, 0
	v_add_u32_e32 v87, s3, v85
	ds_read_b128 v[88:91], v87
	ds_read_b128 v[92:95], v87 offset:4096
	v_add_u32_e32 v87, s3, v86
	ds_read_b128 v[96:99], v87 offset:16384
	ds_read_b128 v[100:103], v87 offset:20480
	s_waitcnt lgkmcnt(0)
	v_add_u32_e32 v87, s3, v83
	ds_read_b128 v[236:239], v87
	ds_read_b128 v[240:243], v87 offset:4096
	v_add_u32_e32 v87, s3, v84
	ds_read_b128 v[244:247], v87 offset:16384
	ds_read_b128 v[248:251], v87 offset:20480
	v_mfma_f32_32x32x16_bf16 v[48:63], v[96:99], v[88:91], v[48:63]
	v_mfma_f32_32x32x16_bf16 v[32:47], v[96:99], v[92:95], v[32:47]
	s_mov_b32 m0, s98
	v_lshl_add_u64 v[254:255], v[76:77], 0, s[100:101]
	global_load_lds_dwordx4 v[254:255], off
	v_mfma_f32_32x32x16_bf16 v[16:31], v[100:103], v[88:91], v[16:31]
	v_mfma_f32_32x32x16_bf16 v[0:15], v[100:103], v[92:95], v[0:15]
	s_add_i32 m0, s98, 0x2000
	v_lshl_add_u64 v[254:255], v[74:75], 0, s[100:101]
	global_load_lds_dwordx4 v[254:255], off
	v_add_u32_e32 v87, s3, v81
	s_waitcnt lgkmcnt(0)
	ds_read_b128 v[88:91], v87
	ds_read_b128 v[92:95], v87 offset:4096
	v_add_u32_e32 v87, s3, v82
	ds_read_b128 v[96:99], v87 offset:16384
	ds_read_b128 v[100:103], v87 offset:20480
	v_mfma_f32_32x32x16_bf16 v[48:63], v[244:247], v[236:239], v[48:63]
	v_mfma_f32_32x32x16_bf16 v[32:47], v[244:247], v[240:243], v[32:47]
	s_add_i32 m0, s98, 0x4000
	v_lshl_add_u64 v[254:255], v[72:73], 0, s[100:101]
	global_load_lds_dwordx4 v[254:255], off
	v_mfma_f32_32x32x16_bf16 v[16:31], v[248:251], v[236:239], v[16:31]
	v_mfma_f32_32x32x16_bf16 v[0:15], v[248:251], v[240:243], v[0:15]
	s_add_i32 m0, s98, 0x6000
	v_lshl_add_u64 v[254:255], v[70:71], 0, s[100:101]
	global_load_lds_dwordx4 v[254:255], off
	v_add_u32_e32 v87, s3, v79
	s_waitcnt lgkmcnt(0)
	ds_read_b128 v[236:239], v87
	ds_read_b128 v[240:243], v87 offset:4096
	v_add_u32_e32 v87, s3, v80
	ds_read_b128 v[244:247], v87 offset:16384
	ds_read_b128 v[248:251], v87 offset:20480
	v_mfma_f32_32x32x16_bf16 v[48:63], v[96:99], v[88:91], v[48:63]
	v_mfma_f32_32x32x16_bf16 v[32:47], v[96:99], v[92:95], v[32:47]
	s_add_i32 m0, s98, 0x8000
	v_lshl_add_u64 v[254:255], v[68:69], 0, s[100:101]
	global_load_lds_dwordx4 v[254:255], off
	v_mfma_f32_32x32x16_bf16 v[16:31], v[100:103], v[88:91], v[16:31]
	v_mfma_f32_32x32x16_bf16 v[0:15], v[100:103], v[92:95], v[0:15]
	s_add_i32 m0, s98, 0xa000
	v_lshl_add_u64 v[254:255], v[66:67], 0, s[100:101]
	global_load_lds_dwordx4 v[254:255], off
	s_add_i32 s3, s14, 0xc000
	s_cmp_lg_u32 s14, 0x18000
	s_cselect_b32 s14, s3, 0
	s_add_i32 s3, s1, 0xc000
	s_waitcnt lgkmcnt(0)
	v_mfma_f32_32x32x16_bf16 v[48:63], v[244:247], v[236:239], v[48:63]
	s_cmp_lg_u32 s1, 0x18000
	s_waitcnt vmcnt(6) lgkmcnt(0)
	s_barrier
	s_cselect_b32 s1, s3, 0
	s_add_u32 s10, s10, 0x80
	s_addc_u32 s11, s11, 0
	v_mfma_f32_32x32x16_bf16 v[32:47], v[244:247], v[240:243], v[32:47]
	s_cmpk_lg_i32 s10, 0x700
	v_mfma_f32_32x32x16_bf16 v[16:31], v[248:251], v[236:239], v[16:31]
	v_mfma_f32_32x32x16_bf16 v[0:15], v[248:251], v[240:243], v[0:15]
	s_cbranch_scc1 .LBB0_308
; DEV int stage_next(int s) { return (s == 2 * GS_STAGE) ? 0 : s + GS_STAGE; }
; template <int WAIT0>
; DEV void gk_main(f32x16 (&acc)[2][2], const GTile& t, int s0) {
;     ...
;   GK_COMPUTE(stc);
;   vm_wait_bar<0>();
;   stc = stage_next(stc);
;   GK_COMPUTE(stc);
;   vm_wait_bar<0>();
	s_add_i32 s0, s14, 0
	v_add_u32_e32 v87, s0, v86
	ds_read_b128 v[66:69], v87 offset:16384
	v_add_u32_e32 v74, s0, v85
	ds_read_b128 v[70:73], v74
	ds_read_b128 v[74:77], v74 offset:4096
	s_waitcnt lgkmcnt(0)
	v_mfma_f32_32x32x16_bf16 v[48:63], v[66:69], v[70:73], v[48:63]
	v_mfma_f32_32x32x16_bf16 v[32:47], v[66:69], v[74:77], v[32:47]
	ds_read_b128 v[66:69], v87 offset:20480
	v_add_u32_e32 v87, s0, v84
	s_waitcnt lgkmcnt(0)
	v_mfma_f32_32x32x16_bf16 v[16:31], v[66:69], v[70:73], v[16:31]
	v_mfma_f32_32x32x16_bf16 v[0:15], v[66:69], v[74:77], v[0:15]
	ds_read_b128 v[66:69], v87 offset:16384
	v_add_u32_e32 v74, s0, v83
	ds_read_b128 v[70:73], v74
	ds_read_b128 v[74:77], v74 offset:4096
	s_waitcnt lgkmcnt(0)
	v_mfma_f32_32x32x16_bf16 v[48:63], v[66:69], v[70:73], v[48:63]
	v_mfma_f32_32x32x16_bf16 v[32:47], v[66:69], v[74:77], v[32:47]
	ds_read_b128 v[66:69], v87 offset:20480
	v_add_u32_e32 v87, s0, v82
	s_waitcnt lgkmcnt(0)
	v_mfma_f32_32x32x16_bf16 v[16:31], v[66:69], v[70:73], v[16:31]
	v_mfma_f32_32x32x16_bf16 v[0:15], v[66:69], v[74:77], v[0:15]
	ds_read_b128 v[66:69], v87 offset:16384
	v_add_u32_e32 v74, s0, v81
	ds_read_b128 v[70:73], v74
	ds_read_b128 v[74:77], v74 offset:4096
	s_waitcnt lgkmcnt(0)
	v_mfma_f32_32x32x16_bf16 v[48:63], v[66:69], v[70:73], v[48:63]
	v_mfma_f32_32x32x16_bf16 v[32:47], v[66:69], v[74:77], v[32:47]
	ds_read_b128 v[66:69], v87 offset:20480
	v_add_u32_e32 v87, s0, v80
	s_waitcnt lgkmcnt(0)
	v_mfma_f32_32x32x16_bf16 v[16:31], v[66:69], v[70:73], v[16:31]
	v_mfma_f32_32x32x16_bf16 v[0:15], v[66:69], v[74:77], v[0:15]
	ds_read_b128 v[66:69], v87 offset:16384
	v_add_u32_e32 v74, s0, v79
	ds_read_b128 v[70:73], v74
	ds_read_b128 v[74:77], v74 offset:4096
	s_add_i32 s0, s14, 0xc000
	s_cmp_lg_u32 s14, 0x18000
	s_cselect_b32 s0, s0, 0
	s_waitcnt lgkmcnt(0)
	v_mfma_f32_32x32x16_bf16 v[48:63], v[66:69], v[70:73], v[48:63]
	s_add_i32 s0, s0, 0
	v_add_u32_e32 v86, s0, v86
	v_add_u32_e32 v84, s0, v84
	v_add_u32_e32 v82, s0, v82
	v_add_u32_e32 v80, s0, v80
	v_mfma_f32_32x32x16_bf16 v[32:47], v[66:69], v[74:77], v[32:47]
	ds_read_b128 v[66:69], v87 offset:20480
	s_waitcnt vmcnt(0) lgkmcnt(0)
	s_barrier
	s_waitcnt lgkmcnt(0)
	v_mfma_f32_32x32x16_bf16 v[16:31], v[66:69], v[70:73], v[16:31]
	v_mfma_f32_32x32x16_bf16 v[0:15], v[66:69], v[74:77], v[0:15]
	ds_read_b128 v[66:69], v86 offset:16384
	v_add_u32_e32 v74, s0, v85
	ds_read_b128 v[70:73], v74
	ds_read_b128 v[74:77], v74 offset:4096
	s_waitcnt lgkmcnt(0)
	v_mfma_f32_32x32x16_bf16 v[48:63], v[66:69], v[70:73], v[48:63]
	v_mfma_f32_32x32x16_bf16 v[32:47], v[66:69], v[74:77], v[32:47]
	ds_read_b128 v[66:69], v86 offset:20480
	s_waitcnt lgkmcnt(0)
	v_mfma_f32_32x32x16_bf16 v[16:31], v[66:69], v[70:73], v[16:31]
	v_mfma_f32_32x32x16_bf16 v[0:15], v[66:69], v[74:77], v[0:15]
	ds_read_b128 v[66:69], v84 offset:16384
	v_add_u32_e32 v74, s0, v83
	ds_read_b128 v[70:73], v74
	ds_read_b128 v[74:77], v74 offset:4096
	s_waitcnt lgkmcnt(0)
	v_mfma_f32_32x32x16_bf16 v[48:63], v[66:69], v[70:73], v[48:63]
	v_mfma_f32_32x32x16_bf16 v[32:47], v[66:69], v[74:77], v[32:47]
	ds_read_b128 v[66:69], v84 offset:20480
	s_waitcnt lgkmcnt(0)
	v_mfma_f32_32x32x16_bf16 v[16:31], v[66:69], v[70:73], v[16:31]
	v_mfma_f32_32x32x16_bf16 v[0:15], v[66:69], v[74:77], v[0:15]
	ds_read_b128 v[66:69], v82 offset:16384
	v_add_u32_e32 v74, s0, v81
	ds_read_b128 v[70:73], v74
	ds_read_b128 v[74:77], v74 offset:4096
	s_waitcnt lgkmcnt(0)
	v_mfma_f32_32x32x16_bf16 v[48:63], v[66:69], v[70:73], v[48:63]
	v_mfma_f32_32x32x16_bf16 v[32:47], v[66:69], v[74:77], v[32:47]
	ds_read_b128 v[66:69], v82 offset:20480
	s_waitcnt lgkmcnt(0)
	v_mfma_f32_32x32x16_bf16 v[16:31], v[66:69], v[70:73], v[16:31]
	v_mfma_f32_32x32x16_bf16 v[0:15], v[66:69], v[74:77], v[0:15]
	ds_read_b128 v[66:69], v80 offset:16384
	v_add_u32_e32 v74, s0, v79
	ds_read_b128 v[70:73], v74
	ds_read_b128 v[74:77], v74 offset:4096
	s_waitcnt lgkmcnt(0)
	v_mfma_f32_32x32x16_bf16 v[48:63], v[66:69], v[70:73], v[48:63]
	v_mfma_f32_32x32x16_bf16 v[32:47], v[66:69], v[74:77], v[32:47]
	ds_read_b128 v[66:69], v80 offset:20480
	s_waitcnt vmcnt(0) lgkmcnt(0)
	s_barrier
	s_waitcnt lgkmcnt(0)
	v_mfma_f32_32x32x16_bf16 v[16:31], v[66:69], v[70:73], v[16:31]
	v_mfma_f32_32x32x16_bf16 v[0:15], v[66:69], v[74:77], v[0:15]
	s_add_i32 s0, s15, 1
	s_mov_b32 s14, s2
	s_cmp_eq_u32 s15, 3
	s_cbranch_scc1 .LBB0_294

; DEV int stage_next(int s) { return (s == 2 * GS_STAGE) ? 0 : s + GS_STAGE; }
; template <int WAIT0>
; DEV void gk_main(f32x16 (&acc)[2][2], const GTile& t, int s0) {
;     ...
;   vm_wait_bar<WAIT0>();
;   int stc = s0, std_ = stage_next(stage_next(s0));
; #pragma nounroll
;   for (int kt = 0; kt < nk - 2; ++kt) {
;     GK_DMA(std_, kt + 2);
;     GK_COMPUTE(stc);
;     vm_wait_bar<6>();
;     stc = stage_next(stc); std_ = stage_next(std_);
;   }
.LBB0_403:
	s_add_i32 s10, s3, s8
	s_mov_b32 s98, s10
	s_add_i32 s10, s2, 0
	v_add_u32_e32 v252, s10, v82
	v_add_u32_e32 v253, s10, v83
	ds_read_b128 v[84:87], v252
	ds_read_b128 v[88:91], v252 offset:4096
	ds_read_b128 v[92:95], v253 offset:16384
	ds_read_b128 v[96:99], v253 offset:20480
	s_waitcnt lgkmcnt(0)
	v_add_u32_e32 v252, s10, v80
	v_add_u32_e32 v253, s10, v81
	ds_read_b128 v[236:239], v252
	ds_read_b128 v[240:243], v252 offset:4096
	ds_read_b128 v[244:247], v253 offset:16384
	ds_read_b128 v[248:251], v253 offset:20480
	v_mfma_f32_32x32x16_bf16 v[48:63], v[92:95], v[84:87], v[48:63]
	v_mfma_f32_32x32x16_bf16 v[32:47], v[92:95], v[88:91], v[32:47]
	s_mov_b32 m0, s98
	v_lshl_add_u64 v[254:255], v[74:75], 0, v[120:121]
	global_load_lds_dwordx4 v[254:255], off
	v_lshl_add_u64 v[74:75], v[74:75], 0, s[96:97]
	v_mfma_f32_32x32x16_bf16 v[16:31], v[96:99], v[84:87], v[16:31]
	v_mfma_f32_32x32x16_bf16 v[0:15], v[96:99], v[88:91], v[0:15]
	s_add_i32 m0, s98, 0x2000
	v_lshl_add_u64 v[254:255], v[72:73], 0, v[120:121]
	global_load_lds_dwordx4 v[254:255], off
	v_lshl_add_u64 v[72:73], v[72:73], 0, s[96:97]
	s_waitcnt lgkmcnt(0)
	v_add_u32_e32 v252, s10, v78
	v_add_u32_e32 v253, s10, v79
	ds_read_b128 v[84:87], v252
	ds_read_b128 v[88:91], v252 offset:4096
	ds_read_b128 v[92:95], v253 offset:16384
	ds_read_b128 v[96:99], v253 offset:20480
	v_mfma_f32_32x32x16_bf16 v[48:63], v[244:247], v[236:239], v[48:63]
	v_mfma_f32_32x32x16_bf16 v[32:47], v[244:247], v[240:243], v[32:47]
	s_add_i32 m0, s98, 0x4000
	v_lshl_add_u64 v[254:255], v[70:71], 0, v[120:121]
	global_load_lds_dwordx4 v[254:255], off
	v_lshl_add_u64 v[70:71], v[70:71], 0, s[96:97]
	v_mfma_f32_32x32x16_bf16 v[16:31], v[248:251], v[236:239], v[16:31]
	v_mfma_f32_32x32x16_bf16 v[0:15], v[248:251], v[240:243], v[0:15]
	s_add_i32 m0, s98, 0x6000
	v_lshl_add_u64 v[254:255], v[68:69], 0, v[120:121]
	global_load_lds_dwordx4 v[254:255], off
	v_lshl_add_u64 v[68:69], v[68:69], 0, s[96:97]
	s_waitcnt lgkmcnt(0)
	v_add_u32_e32 v252, s10, v76
	v_add_u32_e32 v253, s10, v77
	ds_read_b128 v[236:239], v252
	ds_read_b128 v[240:243], v252 offset:4096
	ds_read_b128 v[244:247], v253 offset:16384
	ds_read_b128 v[248:251], v253 offset:20480
	v_mfma_f32_32x32x16_bf16 v[48:63], v[92:95], v[84:87], v[48:63]
	v_mfma_f32_32x32x16_bf16 v[32:47], v[92:95], v[88:91], v[32:47]
	s_add_i32 m0, s98, 0x8000
	v_lshl_add_u64 v[254:255], v[66:67], 0, v[120:121]
	global_load_lds_dwordx4 v[254:255], off
	v_lshl_add_u64 v[66:67], v[66:67], 0, s[96:97]
	v_mfma_f32_32x32x16_bf16 v[16:31], v[96:99], v[84:87], v[16:31]
	v_mfma_f32_32x32x16_bf16 v[0:15], v[96:99], v[88:91], v[0:15]
	s_add_i32 m0, s98, 0xa000
	v_lshl_add_u64 v[254:255], v[64:65], 0, v[120:121]
	global_load_lds_dwordx4 v[254:255], off
	v_lshl_add_u64 v[64:65], v[64:65], 0, s[96:97]
	s_add_i32 s10, s2, 0xc000
	s_cmp_lg_u32 s2, 0x18000
	s_cselect_b32 s2, s10, 0
	s_waitcnt lgkmcnt(0)
	v_mfma_f32_32x32x16_bf16 v[48:63], v[244:247], v[236:239], v[48:63]
	s_add_i32 s10, s8, 0xc000
	s_waitcnt vmcnt(6) lgkmcnt(0)
	s_barrier
	s_cmp_lg_u32 s8, 0x18000
	s_cselect_b32 s8, s10, 0
	s_add_i32 s9, s9, -1
	v_mfma_f32_32x32x16_bf16 v[32:47], v[244:247], v[240:243], v[32:47]
	s_cmp_lg_u32 s9, 0
	v_mfma_f32_32x32x16_bf16 v[16:31], v[248:251], v[236:239], v[16:31]
	v_mfma_f32_32x32x16_bf16 v[0:15], v[248:251], v[240:243], v[0:15]
	s_cbranch_scc1 .LBB0_403
; DEV int stage_next(int s) { return (s == 2 * GS_STAGE) ? 0 : s + GS_STAGE; }
; template <int WAIT0>
; DEV void gk_main(f32x16 (&acc)[2][2], const GTile& t, int s0) {
;     ...
;   GK_COMPUTE(stc);
;   vm_wait_bar<0>();
;   stc = stage_next(stc);
;   GK_COMPUTE(stc);
;   vm_wait_bar<0>();
	s_add_i32 s3, s2, 0
	v_add_u32_e32 v84, s3, v83
	ds_read_b128 v[64:67], v84 offset:16384
	v_add_u32_e32 v72, s3, v82
	ds_read_b128 v[68:71], v72
	ds_read_b128 v[72:75], v72 offset:4096
	s_mov_b64 s[8:9], 0
	s_waitcnt lgkmcnt(0)
	v_mfma_f32_32x32x16_bf16 v[48:63], v[64:67], v[68:71], v[48:63]
	v_mfma_f32_32x32x16_bf16 v[32:47], v[64:67], v[72:75], v[32:47]
	ds_read_b128 v[64:67], v84 offset:20480
	v_add_u32_e32 v84, s3, v81
	s_waitcnt lgkmcnt(0)
	v_mfma_f32_32x32x16_bf16 v[16:31], v[64:67], v[68:71], v[16:31]
	v_mfma_f32_32x32x16_bf16 v[0:15], v[64:67], v[72:75], v[0:15]
	ds_read_b128 v[64:67], v84 offset:16384
	v_add_u32_e32 v72, s3, v80
	ds_read_b128 v[68:71], v72
	ds_read_b128 v[72:75], v72 offset:4096
	s_waitcnt lgkmcnt(0)
	v_mfma_f32_32x32x16_bf16 v[48:63], v[64:67], v[68:71], v[48:63]
	v_mfma_f32_32x32x16_bf16 v[32:47], v[64:67], v[72:75], v[32:47]
	ds_read_b128 v[64:67], v84 offset:20480
	v_add_u32_e32 v84, s3, v79
	s_waitcnt lgkmcnt(0)
	v_mfma_f32_32x32x16_bf16 v[16:31], v[64:67], v[68:71], v[16:31]
	v_mfma_f32_32x32x16_bf16 v[0:15], v[64:67], v[72:75], v[0:15]
	ds_read_b128 v[64:67], v84 offset:16384
	v_add_u32_e32 v72, s3, v78
	ds_read_b128 v[68:71], v72
	ds_read_b128 v[72:75], v72 offset:4096
	s_waitcnt lgkmcnt(0)
	v_mfma_f32_32x32x16_bf16 v[48:63], v[64:67], v[68:71], v[48:63]
	v_mfma_f32_32x32x16_bf16 v[32:47], v[64:67], v[72:75], v[32:47]
	ds_read_b128 v[64:67], v84 offset:20480
	v_add_u32_e32 v84, s3, v77
	s_waitcnt lgkmcnt(0)
	v_mfma_f32_32x32x16_bf16 v[16:31], v[64:67], v[68:71], v[16:31]
	v_mfma_f32_32x32x16_bf16 v[0:15], v[64:67], v[72:75], v[0:15]
	ds_read_b128 v[64:67], v84 offset:16384
	v_add_u32_e32 v72, s3, v76
	ds_read_b128 v[68:71], v72
	ds_read_b128 v[72:75], v72 offset:4096
	s_add_i32 s3, s2, 0xc000
	s_cmp_lg_u32 s2, 0x18000
	s_cselect_b32 s2, s3, 0
	s_waitcnt lgkmcnt(0)
	v_mfma_f32_32x32x16_bf16 v[48:63], v[64:67], v[68:71], v[48:63]
	s_add_i32 s2, s2, 0
	v_add_u32_e32 v83, s2, v83
	v_add_u32_e32 v81, s2, v81
	v_add_u32_e32 v79, s2, v79
	v_add_u32_e32 v77, s2, v77
	v_mfma_f32_32x32x16_bf16 v[32:47], v[64:67], v[72:75], v[32:47]
	ds_read_b128 v[64:67], v84 offset:20480
	s_waitcnt vmcnt(0) lgkmcnt(0)
	s_barrier
	s_waitcnt lgkmcnt(0)
	v_mfma_f32_32x32x16_bf16 v[16:31], v[64:67], v[68:71], v[16:31]
	v_mfma_f32_32x32x16_bf16 v[0:15], v[64:67], v[72:75], v[0:15]
	ds_read_b128 v[64:67], v83 offset:16384
	v_add_u32_e32 v72, s2, v82
	ds_read_b128 v[68:71], v72
	ds_read_b128 v[72:75], v72 offset:4096
	s_waitcnt lgkmcnt(0)
	v_mfma_f32_32x32x16_bf16 v[48:63], v[64:67], v[68:71], v[48:63]
	v_mfma_f32_32x32x16_bf16 v[32:47], v[64:67], v[72:75], v[32:47]
	ds_read_b128 v[64:67], v83 offset:20480
	s_waitcnt lgkmcnt(0)
	v_mfma_f32_32x32x16_bf16 v[16:31], v[64:67], v[68:71], v[16:31]
	v_mfma_f32_32x32x16_bf16 v[0:15], v[64:67], v[72:75], v[0:15]
	ds_read_b128 v[64:67], v81 offset:16384
	v_add_u32_e32 v72, s2, v80
	ds_read_b128 v[68:71], v72
	ds_read_b128 v[72:75], v72 offset:4096
	s_waitcnt lgkmcnt(0)
	v_mfma_f32_32x32x16_bf16 v[48:63], v[64:67], v[68:71], v[48:63]
	v_mfma_f32_32x32x16_bf16 v[32:47], v[64:67], v[72:75], v[32:47]
	ds_read_b128 v[64:67], v81 offset:20480
	s_waitcnt lgkmcnt(0)
	v_mfma_f32_32x32x16_bf16 v[16:31], v[64:67], v[68:71], v[16:31]
	v_mfma_f32_32x32x16_bf16 v[0:15], v[64:67], v[72:75], v[0:15]
	ds_read_b128 v[64:67], v79 offset:16384
	v_add_u32_e32 v72, s2, v78
	ds_read_b128 v[68:71], v72
	ds_read_b128 v[72:75], v72 offset:4096
	s_waitcnt lgkmcnt(0)
	v_mfma_f32_32x32x16_bf16 v[48:63], v[64:67], v[68:71], v[48:63]
	v_mfma_f32_32x32x16_bf16 v[32:47], v[64:67], v[72:75], v[32:47]
	ds_read_b128 v[64:67], v79 offset:20480
	s_waitcnt lgkmcnt(0)
	v_mfma_f32_32x32x16_bf16 v[16:31], v[64:67], v[68:71], v[16:31]
	v_mfma_f32_32x32x16_bf16 v[0:15], v[64:67], v[72:75], v[0:15]
	ds_read_b128 v[64:67], v77 offset:16384
	v_add_u32_e32 v72, s2, v76
	ds_read_b128 v[68:71], v72
	ds_read_b128 v[72:75], v72 offset:4096
	s_waitcnt lgkmcnt(0)
	v_mfma_f32_32x32x16_bf16 v[48:63], v[64:67], v[68:71], v[48:63]
	v_mfma_f32_32x32x16_bf16 v[32:47], v[64:67], v[72:75], v[32:47]
	ds_read_b128 v[64:67], v77 offset:20480
	s_waitcnt vmcnt(0) lgkmcnt(0)
	s_barrier
	s_waitcnt lgkmcnt(0)
	v_mfma_f32_32x32x16_bf16 v[16:31], v[64:67], v[68:71], v[16:31]
	v_mfma_f32_32x32x16_bf16 v[0:15], v[64:67], v[72:75], v[0:15]

; DEV int stage_next(int s) { return (s == 2 * GS_STAGE) ? 0 : s + GS_STAGE; }
; template <int WAIT0>
; DEV void gk_main(f32x16 (&acc)[2][2], const GTile& t, int s0) {
;     ...
;   vm_wait_bar<WAIT0>();
;   int stc = s0, std_ = stage_next(stage_next(s0));
; #pragma nounroll
;   for (int kt = 0; kt < nk - 2; ++kt) {
;     GK_DMA(std_, kt + 2);
;     GK_COMPUTE(stc);
;     vm_wait_bar<6>();
;     stc = stage_next(stc); std_ = stage_next(std_);
;   }
.LBB0_407:
	s_add_i32 s10, s3, s8
	s_mov_b32 s98, s10
	s_add_i32 s10, s2, 0
	v_add_u32_e32 v252, s10, v82
	v_add_u32_e32 v253, s10, v83
	ds_read_b128 v[84:87], v252
	ds_read_b128 v[88:91], v252 offset:4096
	ds_read_b128 v[92:95], v253 offset:16384
	ds_read_b128 v[96:99], v253 offset:20480
	s_waitcnt lgkmcnt(0)
	v_add_u32_e32 v252, s10, v80
	v_add_u32_e32 v253, s10, v81
	ds_read_b128 v[236:239], v252
	ds_read_b128 v[240:243], v252 offset:4096
	ds_read_b128 v[244:247], v253 offset:16384
	ds_read_b128 v[248:251], v253 offset:20480
	v_mfma_f32_32x32x16_bf16 v[48:63], v[92:95], v[84:87], v[48:63]
	v_mfma_f32_32x32x16_bf16 v[32:47], v[92:95], v[88:91], v[32:47]
	s_mov_b32 m0, s98
	v_lshl_add_u64 v[254:255], v[74:75], 0, v[120:121]
	global_load_lds_dwordx4 v[254:255], off
	v_lshl_add_u64 v[74:75], v[74:75], 0, s[96:97]
	v_mfma_f32_32x32x16_bf16 v[16:31], v[96:99], v[84:87], v[16:31]
	v_mfma_f32_32x32x16_bf16 v[0:15], v[96:99], v[88:91], v[0:15]
	s_add_i32 m0, s98, 0x2000
	v_lshl_add_u64 v[254:255], v[72:73], 0, v[120:121]
	global_load_lds_dwordx4 v[254:255], off
	v_lshl_add_u64 v[72:73], v[72:73], 0, s[96:97]
	s_waitcnt lgkmcnt(0)
	v_add_u32_e32 v252, s10, v78
	v_add_u32_e32 v253, s10, v79
	ds_read_b128 v[84:87], v252
	ds_read_b128 v[88:91], v252 offset:4096
	ds_read_b128 v[92:95], v253 offset:16384
	ds_read_b128 v[96:99], v253 offset:20480
	v_mfma_f32_32x32x16_bf16 v[48:63], v[244:247], v[236:239], v[48:63]
	v_mfma_f32_32x32x16_bf16 v[32:47], v[244:247], v[240:243], v[32:47]
	s_add_i32 m0, s98, 0x4000
	v_lshl_add_u64 v[254:255], v[70:71], 0, v[120:121]
	global_load_lds_dwordx4 v[254:255], off
	v_lshl_add_u64 v[70:71], v[70:71], 0, s[96:97]
	v_mfma_f32_32x32x16_bf16 v[16:31], v[248:251], v[236:239], v[16:31]
	v_mfma_f32_32x32x16_bf16 v[0:15], v[248:251], v[240:243], v[0:15]
	s_add_i32 m0, s98, 0x6000
	v_lshl_add_u64 v[254:255], v[68:69], 0, v[120:121]
	global_load_lds_dwordx4 v[254:255], off
	v_lshl_add_u64 v[68:69], v[68:69], 0, s[96:97]
	s_waitcnt lgkmcnt(0)
	v_add_u32_e32 v252, s10, v76
	v_add_u32_e32 v253, s10, v77
	ds_read_b128 v[236:239], v252
	ds_read_b128 v[240:243], v252 offset:4096
	ds_read_b128 v[244:247], v253 offset:16384
	ds_read_b128 v[248:251], v253 offset:20480
	v_mfma_f32_32x32x16_bf16 v[48:63], v[92:95], v[84:87], v[48:63]
	v_mfma_f32_32x32x16_bf16 v[32:47], v[92:95], v[88:91], v[32:47]
	s_add_i32 m0, s98, 0x8000
	v_lshl_add_u64 v[254:255], v[66:67], 0, v[120:121]
	global_load_lds_dwordx4 v[254:255], off
	v_lshl_add_u64 v[66:67], v[66:67], 0, s[96:97]
	v_mfma_f32_32x32x16_bf16 v[16:31], v[96:99], v[84:87], v[16:31]
	v_mfma_f32_32x32x16_bf16 v[0:15], v[96:99], v[88:91], v[0:15]
	s_add_i32 m0, s98, 0xa000
	v_lshl_add_u64 v[254:255], v[64:65], 0, v[120:121]
	global_load_lds_dwordx4 v[254:255], off
	v_lshl_add_u64 v[64:65], v[64:65], 0, s[96:97]
	s_add_i32 s10, s2, 0xc000
	s_cmp_lg_u32 s2, 0x18000
	s_cselect_b32 s2, s10, 0
	s_waitcnt lgkmcnt(0)
	v_mfma_f32_32x32x16_bf16 v[48:63], v[244:247], v[236:239], v[48:63]
	s_add_i32 s10, s8, 0xc000
	s_waitcnt vmcnt(6) lgkmcnt(0)
	s_barrier
	s_cmp_lg_u32 s8, 0x18000
	s_cselect_b32 s8, s10, 0
	s_add_i32 s9, s9, -1
	v_mfma_f32_32x32x16_bf16 v[32:47], v[244:247], v[240:243], v[32:47]
	s_cmp_lg_u32 s9, 0
	v_mfma_f32_32x32x16_bf16 v[16:31], v[248:251], v[236:239], v[16:31]
	v_mfma_f32_32x32x16_bf16 v[0:15], v[248:251], v[240:243], v[0:15]
	s_cbranch_scc1 .LBB0_407
; DEV int stage_next(int s) { return (s == 2 * GS_STAGE) ? 0 : s + GS_STAGE; }
; template <int WAIT0>
; DEV void gk_main(f32x16 (&acc)[2][2], const GTile& t, int s0) {
;     ...
;   GK_COMPUTE(stc);
;   vm_wait_bar<0>();
;   stc = stage_next(stc);
;   GK_COMPUTE(stc);
;   vm_wait_bar<0>();
	s_add_i32 s3, s2, 0
	v_add_u32_e32 v84, s3, v83
	ds_read_b128 v[64:67], v84 offset:16384
	v_add_u32_e32 v72, s3, v82
	ds_read_b128 v[68:71], v72
	ds_read_b128 v[72:75], v72 offset:4096
	s_waitcnt lgkmcnt(0)
	v_mfma_f32_32x32x16_bf16 v[48:63], v[64:67], v[68:71], v[48:63]
	v_mfma_f32_32x32x16_bf16 v[32:47], v[64:67], v[72:75], v[32:47]
	ds_read_b128 v[64:67], v84 offset:20480
	v_add_u32_e32 v84, s3, v81
	s_waitcnt lgkmcnt(0)
	v_mfma_f32_32x32x16_bf16 v[16:31], v[64:67], v[68:71], v[16:31]
	v_mfma_f32_32x32x16_bf16 v[0:15], v[64:67], v[72:75], v[0:15]
	ds_read_b128 v[64:67], v84 offset:16384
	v_add_u32_e32 v72, s3, v80
	ds_read_b128 v[68:71], v72
	ds_read_b128 v[72:75], v72 offset:4096
	s_waitcnt lgkmcnt(0)
	v_mfma_f32_32x32x16_bf16 v[48:63], v[64:67], v[68:71], v[48:63]
	v_mfma_f32_32x32x16_bf16 v[32:47], v[64:67], v[72:75], v[32:47]
	ds_read_b128 v[64:67], v84 offset:20480
	v_add_u32_e32 v84, s3, v79
	s_waitcnt lgkmcnt(0)
	v_mfma_f32_32x32x16_bf16 v[16:31], v[64:67], v[68:71], v[16:31]
	v_mfma_f32_32x32x16_bf16 v[0:15], v[64:67], v[72:75], v[0:15]
	ds_read_b128 v[64:67], v84 offset:16384
	v_add_u32_e32 v72, s3, v78
	ds_read_b128 v[68:71], v72
	ds_read_b128 v[72:75], v72 offset:4096
	s_waitcnt lgkmcnt(0)
	v_mfma_f32_32x32x16_bf16 v[48:63], v[64:67], v[68:71], v[48:63]
	v_mfma_f32_32x32x16_bf16 v[32:47], v[64:67], v[72:75], v[32:47]
	ds_read_b128 v[64:67], v84 offset:20480
	v_add_u32_e32 v84, s3, v77
	s_waitcnt lgkmcnt(0)
	v_mfma_f32_32x32x16_bf16 v[16:31], v[64:67], v[68:71], v[16:31]
	v_mfma_f32_32x32x16_bf16 v[0:15], v[64:67], v[72:75], v[0:15]
	ds_read_b128 v[64:67], v84 offset:16384
	v_add_u32_e32 v72, s3, v76
	ds_read_b128 v[68:71], v72
	ds_read_b128 v[72:75], v72 offset:4096
	s_add_i32 s3, s2, 0xc000
	s_cmp_lg_u32 s2, 0x18000
	s_cselect_b32 s2, s3, 0
	s_waitcnt lgkmcnt(0)
	v_mfma_f32_32x32x16_bf16 v[48:63], v[64:67], v[68:71], v[48:63]
	s_add_i32 s2, s2, 0
	v_add_u32_e32 v83, s2, v83
	v_add_u32_e32 v81, s2, v81
	v_add_u32_e32 v79, s2, v79
	v_add_u32_e32 v77, s2, v77
	v_mfma_f32_32x32x16_bf16 v[32:47], v[64:67], v[72:75], v[32:47]
	ds_read_b128 v[64:67], v84 offset:20480
	s_waitcnt vmcnt(0) lgkmcnt(0)
	s_barrier
	s_waitcnt lgkmcnt(0)
	v_mfma_f32_32x32x16_bf16 v[16:31], v[64:67], v[68:71], v[16:31]
	v_mfma_f32_32x32x16_bf16 v[0:15], v[64:67], v[72:75], v[0:15]
	ds_read_b128 v[64:67], v83 offset:16384
	v_add_u32_e32 v72, s2, v82
	ds_read_b128 v[68:71], v72
	ds_read_b128 v[72:75], v72 offset:4096
	s_waitcnt lgkmcnt(0)
	v_mfma_f32_32x32x16_bf16 v[48:63], v[64:67], v[68:71], v[48:63]
	v_mfma_f32_32x32x16_bf16 v[32:47], v[64:67], v[72:75], v[32:47]
	ds_read_b128 v[64:67], v83 offset:20480
	s_waitcnt lgkmcnt(0)
	v_mfma_f32_32x32x16_bf16 v[16:31], v[64:67], v[68:71], v[16:31]
	v_mfma_f32_32x32x16_bf16 v[0:15], v[64:67], v[72:75], v[0:15]
	ds_read_b128 v[64:67], v81 offset:16384
	v_add_u32_e32 v72, s2, v80
	ds_read_b128 v[68:71], v72
	ds_read_b128 v[72:75], v72 offset:4096
	s_waitcnt lgkmcnt(0)
	v_mfma_f32_32x32x16_bf16 v[48:63], v[64:67], v[68:71], v[48:63]
	v_mfma_f32_32x32x16_bf16 v[32:47], v[64:67], v[72:75], v[32:47]
	ds_read_b128 v[64:67], v81 offset:20480
	s_waitcnt lgkmcnt(0)
	v_mfma_f32_32x32x16_bf16 v[16:31], v[64:67], v[68:71], v[16:31]
	v_mfma_f32_32x32x16_bf16 v[0:15], v[64:67], v[72:75], v[0:15]
	ds_read_b128 v[64:67], v79 offset:16384
	v_add_u32_e32 v72, s2, v78
	ds_read_b128 v[68:71], v72
	ds_read_b128 v[72:75], v72 offset:4096
	s_waitcnt lgkmcnt(0)
	v_mfma_f32_32x32x16_bf16 v[48:63], v[64:67], v[68:71], v[48:63]
	v_mfma_f32_32x32x16_bf16 v[32:47], v[64:67], v[72:75], v[32:47]
	ds_read_b128 v[64:67], v79 offset:20480
	s_waitcnt lgkmcnt(0)
	v_mfma_f32_32x32x16_bf16 v[16:31], v[64:67], v[68:71], v[16:31]
	v_mfma_f32_32x32x16_bf16 v[0:15], v[64:67], v[72:75], v[0:15]
	ds_read_b128 v[64:67], v77 offset:16384
	v_add_u32_e32 v72, s2, v76
	ds_read_b128 v[68:71], v72
	ds_read_b128 v[72:75], v72 offset:4096
	s_waitcnt lgkmcnt(0)
	v_mfma_f32_32x32x16_bf16 v[48:63], v[64:67], v[68:71], v[48:63]
	v_mfma_f32_32x32x16_bf16 v[32:47], v[64:67], v[72:75], v[32:47]
	ds_read_b128 v[64:67], v77 offset:20480
	s_waitcnt vmcnt(0) lgkmcnt(0)
	s_barrier
	s_waitcnt lgkmcnt(0)
	v_mfma_f32_32x32x16_bf16 v[16:31], v[64:67], v[68:71], v[16:31]
	v_mfma_f32_32x32x16_bf16 v[0:15], v[64:67], v[72:75], v[0:15]

; DEV int stage_next(int s) { return (s == 2 * GS_STAGE) ? 0 : s + GS_STAGE; }
; template <int WAIT0>
; DEV void gk_main(f32x16 (&acc)[2][2], const GTile& t, int s0) {
;     ...
;   vm_wait_bar<WAIT0>();
;   int stc = s0, std_ = stage_next(stage_next(s0));
; #pragma nounroll
;   for (int kt = 0; kt < nk - 2; ++kt) {
;     GK_DMA(std_, kt + 2);
;     GK_COMPUTE(stc);
;     vm_wait_bar<6>();
;     stc = stage_next(stc); std_ = stage_next(std_);
;   }
.LBB0_415:
	s_add_i32 s10, s3, s8
	s_mov_b32 s98, s10
	s_add_i32 s10, s2, 0
	v_add_u32_e32 v252, s10, v82
	v_add_u32_e32 v253, s10, v83
	ds_read_b128 v[84:87], v252
	ds_read_b128 v[88:91], v252 offset:4096
	ds_read_b128 v[92:95], v253 offset:16384
	ds_read_b128 v[96:99], v253 offset:20480
	s_waitcnt lgkmcnt(0)
	v_add_u32_e32 v252, s10, v80
	v_add_u32_e32 v253, s10, v81
	ds_read_b128 v[236:239], v252
	ds_read_b128 v[240:243], v252 offset:4096
	ds_read_b128 v[244:247], v253 offset:16384
	ds_read_b128 v[248:251], v253 offset:20480
	v_mfma_f32_32x32x16_bf16 v[48:63], v[92:95], v[84:87], v[48:63]
	v_mfma_f32_32x32x16_bf16 v[32:47], v[92:95], v[88:91], v[32:47]
	s_mov_b32 m0, s98
	v_lshl_add_u64 v[254:255], v[74:75], 0, v[120:121]
	global_load_lds_dwordx4 v[254:255], off
	v_lshl_add_u64 v[74:75], v[74:75], 0, s[96:97]
	v_mfma_f32_32x32x16_bf16 v[16:31], v[96:99], v[84:87], v[16:31]
	v_mfma_f32_32x32x16_bf16 v[0:15], v[96:99], v[88:91], v[0:15]
	s_add_i32 m0, s98, 0x2000
	v_lshl_add_u64 v[254:255], v[72:73], 0, v[120:121]
	global_load_lds_dwordx4 v[254:255], off
	v_lshl_add_u64 v[72:73], v[72:73], 0, s[96:97]
	s_waitcnt lgkmcnt(0)
	v_add_u32_e32 v252, s10, v78
	v_add_u32_e32 v253, s10, v79
	ds_read_b128 v[84:87], v252
	ds_read_b128 v[88:91], v252 offset:4096
	ds_read_b128 v[92:95], v253 offset:16384
	ds_read_b128 v[96:99], v253 offset:20480
	v_mfma_f32_32x32x16_bf16 v[48:63], v[244:247], v[236:239], v[48:63]
	v_mfma_f32_32x32x16_bf16 v[32:47], v[244:247], v[240:243], v[32:47]
	s_add_i32 m0, s98, 0x4000
	v_lshl_add_u64 v[254:255], v[70:71], 0, v[120:121]
	global_load_lds_dwordx4 v[254:255], off
	v_lshl_add_u64 v[70:71], v[70:71], 0, s[96:97]
	v_mfma_f32_32x32x16_bf16 v[16:31], v[248:251], v[236:239], v[16:31]
	v_mfma_f32_32x32x16_bf16 v[0:15], v[248:251], v[240:243], v[0:15]
	s_add_i32 m0, s98, 0x6000
	v_lshl_add_u64 v[254:255], v[68:69], 0, v[120:121]
	global_load_lds_dwordx4 v[254:255], off
	v_lshl_add_u64 v[68:69], v[68:69], 0, s[96:97]
	s_waitcnt lgkmcnt(0)
	v_add_u32_e32 v252, s10, v76
	v_add_u32_e32 v253, s10, v77
	ds_read_b128 v[236:239], v252
	ds_read_b128 v[240:243], v252 offset:4096
	ds_read_b128 v[244:247], v253 offset:16384
	ds_read_b128 v[248:251], v253 offset:20480
	v_mfma_f32_32x32x16_bf16 v[48:63], v[92:95], v[84:87], v[48:63]
	v_mfma_f32_32x32x16_bf16 v[32:47], v[92:95], v[88:91], v[32:47]
	s_add_i32 m0, s98, 0x8000
	v_lshl_add_u64 v[254:255], v[66:67], 0, v[120:121]
	global_load_lds_dwordx4 v[254:255], off
	v_lshl_add_u64 v[66:67], v[66:67], 0, s[96:97]
	v_mfma_f32_32x32x16_bf16 v[16:31], v[96:99], v[84:87], v[16:31]
	v_mfma_f32_32x32x16_bf16 v[0:15], v[96:99], v[88:91], v[0:15]
	s_add_i32 m0, s98, 0xa000
	v_lshl_add_u64 v[254:255], v[64:65], 0, v[120:121]
	global_load_lds_dwordx4 v[254:255], off
	v_lshl_add_u64 v[64:65], v[64:65], 0, s[96:97]
	s_add_i32 s10, s2, 0xc000
	s_cmp_lg_u32 s2, 0x18000
	s_cselect_b32 s2, s10, 0
	s_waitcnt lgkmcnt(0)
	v_mfma_f32_32x32x16_bf16 v[48:63], v[244:247], v[236:239], v[48:63]
	s_add_i32 s10, s8, 0xc000
	s_waitcnt vmcnt(6) lgkmcnt(0)
	s_barrier
	s_cmp_lg_u32 s8, 0x18000
	s_cselect_b32 s8, s10, 0
	s_add_i32 s9, s9, -1
	v_mfma_f32_32x32x16_bf16 v[32:47], v[244:247], v[240:243], v[32:47]
	s_cmp_lg_u32 s9, 0
	v_mfma_f32_32x32x16_bf16 v[16:31], v[248:251], v[236:239], v[16:31]
	v_mfma_f32_32x32x16_bf16 v[0:15], v[248:251], v[240:243], v[0:15]
	s_cbranch_scc1 .LBB0_415
; DEV int stage_next(int s) { return (s == 2 * GS_STAGE) ? 0 : s + GS_STAGE; }
; template <int WAIT0>
; DEV void gk_main(f32x16 (&acc)[2][2], const GTile& t, int s0) {
;     ...
;   GK_COMPUTE(stc);
;   vm_wait_bar<0>();
;   stc = stage_next(stc);
;   GK_COMPUTE(stc);
;   vm_wait_bar<0>();
	s_add_i32 s3, s2, 0
	v_add_u32_e32 v84, s3, v83
	ds_read_b128 v[64:67], v84 offset:16384
	v_add_u32_e32 v72, s3, v82
	ds_read_b128 v[68:71], v72
	ds_read_b128 v[72:75], v72 offset:4096
	s_waitcnt lgkmcnt(0)
	v_mfma_f32_32x32x16_bf16 v[48:63], v[64:67], v[68:71], v[48:63]
	v_mfma_f32_32x32x16_bf16 v[32:47], v[64:67], v[72:75], v[32:47]
	ds_read_b128 v[64:67], v84 offset:20480
	v_add_u32_e32 v84, s3, v81
	s_waitcnt lgkmcnt(0)
	v_mfma_f32_32x32x16_bf16 v[16:31], v[64:67], v[68:71], v[16:31]
	v_mfma_f32_32x32x16_bf16 v[0:15], v[64:67], v[72:75], v[0:15]
	ds_read_b128 v[64:67], v84 offset:16384
	v_add_u32_e32 v72, s3, v80
	ds_read_b128 v[68:71], v72
	ds_read_b128 v[72:75], v72 offset:4096
	s_waitcnt lgkmcnt(0)
	v_mfma_f32_32x32x16_bf16 v[48:63], v[64:67], v[68:71], v[48:63]
	v_mfma_f32_32x32x16_bf16 v[32:47], v[64:67], v[72:75], v[32:47]
	ds_read_b128 v[64:67], v84 offset:20480
	v_add_u32_e32 v84, s3, v79
	s_waitcnt lgkmcnt(0)
	v_mfma_f32_32x32x16_bf16 v[16:31], v[64:67], v[68:71], v[16:31]
	v_mfma_f32_32x32x16_bf16 v[0:15], v[64:67], v[72:75], v[0:15]
	ds_read_b128 v[64:67], v84 offset:16384
	v_add_u32_e32 v72, s3, v78
	ds_read_b128 v[68:71], v72
	ds_read_b128 v[72:75], v72 offset:4096
	s_waitcnt lgkmcnt(0)
	v_mfma_f32_32x32x16_bf16 v[48:63], v[64:67], v[68:71], v[48:63]
	v_mfma_f32_32x32x16_bf16 v[32:47], v[64:67], v[72:75], v[32:47]
	ds_read_b128 v[64:67], v84 offset:20480
	v_add_u32_e32 v84, s3, v77
	s_waitcnt lgkmcnt(0)
	v_mfma_f32_32x32x16_bf16 v[16:31], v[64:67], v[68:71], v[16:31]
	v_mfma_f32_32x32x16_bf16 v[0:15], v[64:67], v[72:75], v[0:15]
	ds_read_b128 v[64:67], v84 offset:16384
	v_add_u32_e32 v72, s3, v76
	ds_read_b128 v[68:71], v72
	ds_read_b128 v[72:75], v72 offset:4096
	s_add_i32 s3, s2, 0xc000
	s_cmp_lg_u32 s2, 0x18000
	s_cselect_b32 s2, s3, 0
	s_waitcnt lgkmcnt(0)
	v_mfma_f32_32x32x16_bf16 v[48:63], v[64:67], v[68:71], v[48:63]
	s_add_i32 s2, s2, 0
	v_add_u32_e32 v83, s2, v83
	v_add_u32_e32 v81, s2, v81
	v_add_u32_e32 v79, s2, v79
	v_add_u32_e32 v77, s2, v77
	v_mfma_f32_32x32x16_bf16 v[32:47], v[64:67], v[72:75], v[32:47]
	ds_read_b128 v[64:67], v84 offset:20480
	s_waitcnt vmcnt(0) lgkmcnt(0)
	s_barrier
	s_waitcnt lgkmcnt(0)
	v_mfma_f32_32x32x16_bf16 v[16:31], v[64:67], v[68:71], v[16:31]
	v_mfma_f32_32x32x16_bf16 v[0:15], v[64:67], v[72:75], v[0:15]
	ds_read_b128 v[64:67], v83 offset:16384
	v_add_u32_e32 v72, s2, v82
	ds_read_b128 v[68:71], v72
	ds_read_b128 v[72:75], v72 offset:4096
	s_waitcnt lgkmcnt(0)
	v_mfma_f32_32x32x16_bf16 v[48:63], v[64:67], v[68:71], v[48:63]
	v_mfma_f32_32x32x16_bf16 v[32:47], v[64:67], v[72:75], v[32:47]
	ds_read_b128 v[64:67], v83 offset:20480
	s_waitcnt lgkmcnt(0)
	v_mfma_f32_32x32x16_bf16 v[16:31], v[64:67], v[68:71], v[16:31]
	v_mfma_f32_32x32x16_bf16 v[0:15], v[64:67], v[72:75], v[0:15]
	ds_read_b128 v[64:67], v81 offset:16384
	v_add_u32_e32 v72, s2, v80
	ds_read_b128 v[68:71], v72
	ds_read_b128 v[72:75], v72 offset:4096
	s_waitcnt lgkmcnt(0)
	v_mfma_f32_32x32x16_bf16 v[48:63], v[64:67], v[68:71], v[48:63]
	v_mfma_f32_32x32x16_bf16 v[32:47], v[64:67], v[72:75], v[32:47]
	ds_read_b128 v[64:67], v81 offset:20480
	s_waitcnt lgkmcnt(0)
	v_mfma_f32_32x32x16_bf16 v[16:31], v[64:67], v[68:71], v[16:31]
	v_mfma_f32_32x32x16_bf16 v[0:15], v[64:67], v[72:75], v[0:15]
	ds_read_b128 v[64:67], v79 offset:16384
	v_add_u32_e32 v72, s2, v78
	ds_read_b128 v[68:71], v72
	ds_read_b128 v[72:75], v72 offset:4096
	s_waitcnt lgkmcnt(0)
	v_mfma_f32_32x32x16_bf16 v[48:63], v[64:67], v[68:71], v[48:63]
	v_mfma_f32_32x32x16_bf16 v[32:47], v[64:67], v[72:75], v[32:47]
	ds_read_b128 v[64:67], v79 offset:20480
	s_waitcnt lgkmcnt(0)
	v_mfma_f32_32x32x16_bf16 v[16:31], v[64:67], v[68:71], v[16:31]
	v_mfma_f32_32x32x16_bf16 v[0:15], v[64:67], v[72:75], v[0:15]
	ds_read_b128 v[64:67], v77 offset:16384
	v_add_u32_e32 v72, s2, v76
	ds_read_b128 v[68:71], v72
	ds_read_b128 v[72:75], v72 offset:4096
	s_waitcnt lgkmcnt(0)
	v_mfma_f32_32x32x16_bf16 v[48:63], v[64:67], v[68:71], v[48:63]
	v_mfma_f32_32x32x16_bf16 v[32:47], v[64:67], v[72:75], v[32:47]
	ds_read_b128 v[64:67], v77 offset:20480
	s_waitcnt vmcnt(0) lgkmcnt(0)
	s_barrier
	s_waitcnt lgkmcnt(0)
	v_mfma_f32_32x32x16_bf16 v[16:31], v[64:67], v[68:71], v[16:31]
	v_mfma_f32_32x32x16_bf16 v[0:15], v[64:67], v[72:75], v[0:15]
	s_add_i32 s2, s19, 1
	s_cmp_eq_u32 s19, 7
	s_mov_b64 s[8:9], 0
	s_cbranch_scc1 .LBB0_411

; DEV int stage_next(int s) { return (s == 2 * GS_STAGE) ? 0 : s + GS_STAGE; }
; template <int WAIT0>
; DEV void gk_main(f32x16 (&acc)[2][2], const GTile& t, int s0) {
;     ...
;   vm_wait_bar<WAIT0>();
;   int stc = s0, std_ = stage_next(stage_next(s0));
; #pragma nounroll
;   for (int kt = 0; kt < nk - 2; ++kt) {
;     GK_DMA(std_, kt + 2);
;     GK_COMPUTE(stc);
;     vm_wait_bar<6>();
;     stc = stage_next(stc); std_ = stage_next(std_);
;   }
.LBB0_437:
	s_add_i32 s12, s10, s11
	s_mov_b32 s98, s12
	s_mov_b64 s[100:101], s[6:7]
	s_add_i32 s12, s3, 0
	v_add_u32_e32 v252, s12, v82
	v_add_u32_e32 v253, s12, v83
	ds_read_b128 v[84:87], v252
	ds_read_b128 v[88:91], v252 offset:4096
	ds_read_b128 v[92:95], v253 offset:16384
	ds_read_b128 v[96:99], v253 offset:20480
	s_waitcnt lgkmcnt(0)
	v_add_u32_e32 v252, s12, v80
	v_add_u32_e32 v253, s12, v81
	ds_read_b128 v[236:239], v252
	ds_read_b128 v[240:243], v252 offset:4096
	ds_read_b128 v[244:247], v253 offset:16384
	ds_read_b128 v[248:251], v253 offset:20480
	v_mfma_f32_32x32x16_bf16 v[48:63], v[92:95], v[84:87], v[48:63]
	v_mfma_f32_32x32x16_bf16 v[16:31], v[92:95], v[88:91], v[16:31]
	s_mov_b32 m0, s98
	v_lshl_add_u64 v[254:255], v[74:75], 0, s[100:101]
	global_load_lds_dwordx4 v[254:255], off
	v_mfma_f32_32x32x16_bf16 v[32:47], v[96:99], v[84:87], v[32:47]
	v_mfma_f32_32x32x16_bf16 v[0:15], v[96:99], v[88:91], v[0:15]
	s_add_i32 m0, s98, 0x2000
	v_lshl_add_u64 v[254:255], v[72:73], 0, s[100:101]
	global_load_lds_dwordx4 v[254:255], off
	s_waitcnt lgkmcnt(0)
	v_add_u32_e32 v252, s12, v78
	v_add_u32_e32 v253, s12, v79
	ds_read_b128 v[84:87], v252
	ds_read_b128 v[88:91], v252 offset:4096
	ds_read_b128 v[92:95], v253 offset:16384
	ds_read_b128 v[96:99], v253 offset:20480
	v_mfma_f32_32x32x16_bf16 v[48:63], v[244:247], v[236:239], v[48:63]
	v_mfma_f32_32x32x16_bf16 v[16:31], v[244:247], v[240:243], v[16:31]
	s_add_i32 m0, s98, 0x4000
	v_lshl_add_u64 v[254:255], v[70:71], 0, s[100:101]
	global_load_lds_dwordx4 v[254:255], off
	v_mfma_f32_32x32x16_bf16 v[32:47], v[248:251], v[236:239], v[32:47]
	v_mfma_f32_32x32x16_bf16 v[0:15], v[248:251], v[240:243], v[0:15]
	s_add_i32 m0, s98, 0x6000
	v_lshl_add_u64 v[254:255], v[68:69], 0, s[100:101]
	global_load_lds_dwordx4 v[254:255], off
	s_waitcnt lgkmcnt(0)
	v_add_u32_e32 v252, s12, v76
	v_add_u32_e32 v253, s12, v77
	ds_read_b128 v[236:239], v252
	ds_read_b128 v[240:243], v252 offset:4096
	ds_read_b128 v[244:247], v253 offset:16384
	ds_read_b128 v[248:251], v253 offset:20480
	v_mfma_f32_32x32x16_bf16 v[48:63], v[92:95], v[84:87], v[48:63]
	v_mfma_f32_32x32x16_bf16 v[16:31], v[92:95], v[88:91], v[16:31]
	s_add_i32 m0, s98, 0x8000
	v_lshl_add_u64 v[254:255], v[66:67], 0, s[100:101]
	global_load_lds_dwordx4 v[254:255], off
	v_mfma_f32_32x32x16_bf16 v[32:47], v[96:99], v[84:87], v[32:47]
	v_mfma_f32_32x32x16_bf16 v[0:15], v[96:99], v[88:91], v[0:15]
	s_add_i32 m0, s98, 0xa000
	v_lshl_add_u64 v[254:255], v[64:65], 0, s[100:101]
	global_load_lds_dwordx4 v[254:255], off
	s_add_i32 s12, s3, 0xc000
	s_cmp_lg_u32 s3, 0x18000
	s_cselect_b32 s3, s12, 0
	s_waitcnt lgkmcnt(0)
	v_mfma_f32_32x32x16_bf16 v[48:63], v[244:247], v[236:239], v[48:63]
	s_add_i32 s12, s11, 0xc000
	s_cmp_lg_u32 s11, 0x18000
	s_waitcnt vmcnt(6) lgkmcnt(0)
	s_barrier
	s_cselect_b32 s11, s12, 0
	s_add_u32 s6, s6, 0x80
	v_mfma_f32_32x32x16_bf16 v[16:31], v[244:247], v[240:243], v[16:31]
	s_addc_u32 s7, s7, 0
	s_cmpk_lg_i32 s6, 0x700
	v_mfma_f32_32x32x16_bf16 v[32:47], v[248:251], v[236:239], v[32:47]
	v_mfma_f32_32x32x16_bf16 v[0:15], v[248:251], v[240:243], v[0:15]
	s_cbranch_scc1 .LBB0_437
; DEV int stage_next(int s) { return (s == 2 * GS_STAGE) ? 0 : s + GS_STAGE; }
; template <int WAIT0>
; DEV void gk_main(f32x16 (&acc)[2][2], const GTile& t, int s0) {
;     ...
;   GK_COMPUTE(stc);
;   vm_wait_bar<0>();
;   stc = stage_next(stc);
;   GK_COMPUTE(stc);
;   vm_wait_bar<0>();
	s_add_i32 s6, s3, 0
	v_add_u32_e32 v84, s6, v83
	ds_read_b128 v[64:67], v84 offset:16384
	v_add_u32_e32 v72, s6, v82
	ds_read_b128 v[68:71], v72
	ds_read_b128 v[72:75], v72 offset:4096
	s_waitcnt lgkmcnt(0)
	v_mfma_f32_32x32x16_bf16 v[48:63], v[64:67], v[68:71], v[48:63]
	v_mfma_f32_32x32x16_bf16 v[16:31], v[64:67], v[72:75], v[16:31]
	ds_read_b128 v[64:67], v84 offset:20480
	v_add_u32_e32 v84, s6, v81
	s_waitcnt lgkmcnt(0)
	v_mfma_f32_32x32x16_bf16 v[32:47], v[64:67], v[68:71], v[32:47]
	v_mfma_f32_32x32x16_bf16 v[0:15], v[64:67], v[72:75], v[0:15]
	ds_read_b128 v[64:67], v84 offset:16384
	v_add_u32_e32 v72, s6, v80
	ds_read_b128 v[68:71], v72
	ds_read_b128 v[72:75], v72 offset:4096
	s_waitcnt lgkmcnt(0)
	v_mfma_f32_32x32x16_bf16 v[48:63], v[64:67], v[68:71], v[48:63]
	v_mfma_f32_32x32x16_bf16 v[16:31], v[64:67], v[72:75], v[16:31]
	ds_read_b128 v[64:67], v84 offset:20480
	v_add_u32_e32 v84, s6, v79
	s_waitcnt lgkmcnt(0)
	v_mfma_f32_32x32x16_bf16 v[32:47], v[64:67], v[68:71], v[32:47]
	v_mfma_f32_32x32x16_bf16 v[0:15], v[64:67], v[72:75], v[0:15]
	ds_read_b128 v[64:67], v84 offset:16384
	v_add_u32_e32 v72, s6, v78
	ds_read_b128 v[68:71], v72
	ds_read_b128 v[72:75], v72 offset:4096
	s_waitcnt lgkmcnt(0)
	v_mfma_f32_32x32x16_bf16 v[48:63], v[64:67], v[68:71], v[48:63]
	v_mfma_f32_32x32x16_bf16 v[16:31], v[64:67], v[72:75], v[16:31]
	ds_read_b128 v[64:67], v84 offset:20480
	v_add_u32_e32 v84, s6, v77
	s_waitcnt lgkmcnt(0)
	v_mfma_f32_32x32x16_bf16 v[32:47], v[64:67], v[68:71], v[32:47]
	v_mfma_f32_32x32x16_bf16 v[0:15], v[64:67], v[72:75], v[0:15]
	ds_read_b128 v[64:67], v84 offset:16384
	v_add_u32_e32 v72, s6, v76
	ds_read_b128 v[68:71], v72
	ds_read_b128 v[72:75], v72 offset:4096
	s_add_i32 s6, s3, 0xc000
	s_cmp_lg_u32 s3, 0x18000
	s_cselect_b32 s3, s6, 0
	s_waitcnt lgkmcnt(0)
	v_mfma_f32_32x32x16_bf16 v[48:63], v[64:67], v[68:71], v[48:63]
	s_add_i32 s3, s3, 0
	v_add_u32_e32 v83, s3, v83
	v_add_u32_e32 v81, s3, v81
	v_add_u32_e32 v79, s3, v79
	v_add_u32_e32 v77, s3, v77
	v_mfma_f32_32x32x16_bf16 v[16:31], v[64:67], v[72:75], v[16:31]
	ds_read_b128 v[64:67], v84 offset:20480
	s_waitcnt vmcnt(0) lgkmcnt(0)
	s_barrier
	s_waitcnt lgkmcnt(0)
	v_mfma_f32_32x32x16_bf16 v[32:47], v[64:67], v[68:71], v[32:47]
	v_mfma_f32_32x32x16_bf16 v[0:15], v[64:67], v[72:75], v[0:15]
	ds_read_b128 v[64:67], v83 offset:16384
	v_add_u32_e32 v72, s3, v82
	ds_read_b128 v[68:71], v72
	ds_read_b128 v[72:75], v72 offset:4096
	s_waitcnt lgkmcnt(0)
	v_mfma_f32_32x32x16_bf16 v[48:63], v[64:67], v[68:71], v[48:63]
	v_mfma_f32_32x32x16_bf16 v[16:31], v[64:67], v[72:75], v[16:31]
	ds_read_b128 v[64:67], v83 offset:20480
	s_waitcnt lgkmcnt(0)
	v_mfma_f32_32x32x16_bf16 v[32:47], v[64:67], v[68:71], v[32:47]
	v_mfma_f32_32x32x16_bf16 v[0:15], v[64:67], v[72:75], v[0:15]
	ds_read_b128 v[64:67], v81 offset:16384
	v_add_u32_e32 v72, s3, v80
	ds_read_b128 v[68:71], v72
	ds_read_b128 v[72:75], v72 offset:4096
	s_waitcnt lgkmcnt(0)
	v_mfma_f32_32x32x16_bf16 v[48:63], v[64:67], v[68:71], v[48:63]
	v_mfma_f32_32x32x16_bf16 v[16:31], v[64:67], v[72:75], v[16:31]
	ds_read_b128 v[64:67], v81 offset:20480
	s_waitcnt lgkmcnt(0)
	v_mfma_f32_32x32x16_bf16 v[32:47], v[64:67], v[68:71], v[32:47]
	v_mfma_f32_32x32x16_bf16 v[0:15], v[64:67], v[72:75], v[0:15]
	ds_read_b128 v[64:67], v79 offset:16384
	v_add_u32_e32 v72, s3, v78
	ds_read_b128 v[68:71], v72
	ds_read_b128 v[72:75], v72 offset:4096
	s_waitcnt lgkmcnt(0)
	v_mfma_f32_32x32x16_bf16 v[48:63], v[64:67], v[68:71], v[48:63]
	v_mfma_f32_32x32x16_bf16 v[16:31], v[64:67], v[72:75], v[16:31]
	ds_read_b128 v[64:67], v79 offset:20480
	s_waitcnt lgkmcnt(0)
	v_mfma_f32_32x32x16_bf16 v[32:47], v[64:67], v[68:71], v[32:47]
	v_mfma_f32_32x32x16_bf16 v[0:15], v[64:67], v[72:75], v[0:15]
	ds_read_b128 v[64:67], v77 offset:16384
	v_add_u32_e32 v72, s3, v76
	ds_read_b128 v[68:71], v72
	ds_read_b128 v[72:75], v72 offset:4096
	s_waitcnt lgkmcnt(0)
	v_mfma_f32_32x32x16_bf16 v[48:63], v[64:67], v[68:71], v[48:63]
	v_mfma_f32_32x32x16_bf16 v[16:31], v[64:67], v[72:75], v[16:31]
	ds_read_b128 v[64:67], v77 offset:20480
	s_waitcnt vmcnt(0) lgkmcnt(0)
	s_barrier
	s_waitcnt lgkmcnt(0)
	v_mfma_f32_32x32x16_bf16 v[32:47], v[64:67], v[68:71], v[32:47]
	v_mfma_f32_32x32x16_bf16 v[0:15], v[64:67], v[72:75], v[0:15]
	s_add_i32 s3, s2, 1
	s_cmp_eq_u32 s2, 7
	s_cbranch_scc1 .LBB0_423

; DEV int stage_next(int s) { return (s == 2 * GS_STAGE) ? 0 : s + GS_STAGE; }
; template <int WAIT0>
; DEV void gk_main(f32x16 (&acc)[2][2], const GTile& t, int s0) {
;     ...
;   vm_wait_bar<WAIT0>();
;   int stc = s0, std_ = stage_next(stage_next(s0));
; #pragma nounroll
;   for (int kt = 0; kt < nk - 2; ++kt) {
;     GK_DMA(std_, kt + 2);
;     GK_COMPUTE(stc);
;     vm_wait_bar<6>();
;     stc = stage_next(stc); std_ = stage_next(std_);
;   }
.LBB0_842:
	s_add_i32 s10, s2, s3
	s_mov_b32 s98, s10
	s_add_i32 s11, s9, 0
	v_add_u32_e32 v253, s11, v81
	v_add_u32_e32 v252, s11, v83
	ds_read_b128 v[84:87], v252 offset:16384
	ds_read_b128 v[88:91], v253
	ds_read_b128 v[92:95], v253 offset:4096
	ds_read_b128 v[96:99], v252 offset:20480
	s_waitcnt lgkmcnt(0)
	v_add_u32_e32 v101, s11, v82
	v_add_u32_e32 v100, s11, v79
	s_add_i32 s10, s9, 0xc000
	s_cmp_lg_u32 s9, 0x18000
	s_cselect_b32 s9, s10, 0
	s_add_i32 s10, s3, 0xc000
	s_cmp_lg_u32 s3, 0x18000
	s_cselect_b32 s3, s10, 0
	s_add_i32 s8, s8, -1
	ds_read_b128 v[236:239], v101 offset:16384
	ds_read_b128 v[240:243], v100
	ds_read_b128 v[244:247], v100 offset:4096
	ds_read_b128 v[248:251], v101 offset:20480
	v_mfma_f32_32x32x16_bf16 v[48:63], v[84:87], v[88:91], v[48:63]
	v_mfma_f32_32x32x16_bf16 v[32:47], v[84:87], v[92:95], v[32:47]
	s_mov_b32 m0, s98
	v_lshl_add_u64 v[254:255], v[74:75], 0, v[120:121]
	global_load_lds_dwordx4 v[254:255], off
	v_lshl_add_u64 v[74:75], v[74:75], 0, s[94:95]
	v_mfma_f32_32x32x16_bf16 v[16:31], v[96:99], v[88:91], v[16:31]
	v_mfma_f32_32x32x16_bf16 v[0:15], v[96:99], v[92:95], v[0:15]
	s_add_i32 m0, s98, 0x2000
	v_lshl_add_u64 v[254:255], v[72:73], 0, v[120:121]
	global_load_lds_dwordx4 v[254:255], off
	v_lshl_add_u64 v[72:73], v[72:73], 0, s[94:95]
	v_add_u32_e32 v101, s11, v80
	v_add_u32_e32 v100, s11, v77
	s_waitcnt lgkmcnt(0)
	ds_read_b128 v[84:87], v101 offset:16384
	ds_read_b128 v[88:91], v100
	ds_read_b128 v[92:95], v100 offset:4096
	ds_read_b128 v[96:99], v101 offset:20480
	v_mfma_f32_32x32x16_bf16 v[48:63], v[236:239], v[240:243], v[48:63]
	v_mfma_f32_32x32x16_bf16 v[32:47], v[236:239], v[244:247], v[32:47]
	s_add_i32 m0, s98, 0x4000
	v_lshl_add_u64 v[254:255], v[70:71], 0, v[120:121]
	global_load_lds_dwordx4 v[254:255], off
	v_lshl_add_u64 v[70:71], v[70:71], 0, s[94:95]
	v_mfma_f32_32x32x16_bf16 v[16:31], v[248:251], v[240:243], v[16:31]
	v_mfma_f32_32x32x16_bf16 v[0:15], v[248:251], v[244:247], v[0:15]
	s_add_i32 m0, s98, 0x6000
	v_lshl_add_u64 v[254:255], v[68:69], 0, v[120:121]
	global_load_lds_dwordx4 v[254:255], off
	v_lshl_add_u64 v[68:69], v[68:69], 0, s[94:95]
	v_add_u32_e32 v101, s11, v78
	v_add_u32_e32 v100, s11, v76
	s_waitcnt lgkmcnt(0)
	ds_read_b128 v[236:239], v101 offset:16384
	ds_read_b128 v[240:243], v100
	ds_read_b128 v[244:247], v100 offset:4096
	ds_read_b128 v[248:251], v101 offset:20480
	v_mfma_f32_32x32x16_bf16 v[48:63], v[84:87], v[88:91], v[48:63]
	v_mfma_f32_32x32x16_bf16 v[32:47], v[84:87], v[92:95], v[32:47]
	s_add_i32 m0, s98, 0x8000
	v_lshl_add_u64 v[254:255], v[66:67], 0, v[120:121]
	global_load_lds_dwordx4 v[254:255], off
	v_lshl_add_u64 v[66:67], v[66:67], 0, s[94:95]
	v_mfma_f32_32x32x16_bf16 v[16:31], v[96:99], v[88:91], v[16:31]
	v_mfma_f32_32x32x16_bf16 v[0:15], v[96:99], v[92:95], v[0:15]
	s_add_i32 m0, s98, 0xa000
	v_lshl_add_u64 v[254:255], v[64:65], 0, v[120:121]
	global_load_lds_dwordx4 v[254:255], off
	v_lshl_add_u64 v[64:65], v[64:65], 0, s[94:95]
	s_waitcnt vmcnt(6) lgkmcnt(0)
	s_barrier
	s_waitcnt lgkmcnt(0)
	v_mfma_f32_32x32x16_bf16 v[48:63], v[236:239], v[240:243], v[48:63]
	v_mfma_f32_32x32x16_bf16 v[32:47], v[236:239], v[244:247], v[32:47]
	v_mfma_f32_32x32x16_bf16 v[16:31], v[248:251], v[240:243], v[16:31]
	v_mfma_f32_32x32x16_bf16 v[0:15], v[248:251], v[244:247], v[0:15]
	s_cmp_lg_u32 s8, 0
	s_cbranch_scc1 .LBB0_842
; DEV int stage_next(int s) { return (s == 2 * GS_STAGE) ? 0 : s + GS_STAGE; }
; template <int WAIT0>
; DEV void gk_main(f32x16 (&acc)[2][2], const GTile& t, int s0) {
;     ...
;   GK_COMPUTE(stc);
;   vm_wait_bar<0>();
;   stc = stage_next(stc);
;   GK_COMPUTE(stc);
;   vm_wait_bar<0>();
	s_add_i32 s2, s9, 0
	v_add_u32_e32 v84, s2, v83
	ds_read_b128 v[64:67], v84 offset:16384
	v_add_u32_e32 v72, s2, v81
	ds_read_b128 v[68:71], v72
	ds_read_b128 v[72:75], v72 offset:4096
	ds_read_b128 v[84:87], v84 offset:20480
	s_waitcnt lgkmcnt(0)
	v_mfma_f32_32x32x16_bf16 v[16:31], v[84:87], v[68:71], v[16:31]
	v_mfma_f32_32x32x16_bf16 v[0:15], v[84:87], v[72:75], v[0:15]
	v_add_u32_e32 v84, s2, v82
	v_mfma_f32_32x32x16_bf16 v[48:63], v[64:67], v[68:71], v[48:63]
	v_mfma_f32_32x32x16_bf16 v[32:47], v[64:67], v[72:75], v[32:47]
	ds_read_b128 v[64:67], v84 offset:16384
	v_add_u32_e32 v72, s2, v79
	ds_read_b128 v[68:71], v72
	ds_read_b128 v[72:75], v72 offset:4096
	ds_read_b128 v[84:87], v84 offset:20480
	s_waitcnt lgkmcnt(0)
	v_mfma_f32_32x32x16_bf16 v[16:31], v[84:87], v[68:71], v[16:31]
	v_mfma_f32_32x32x16_bf16 v[0:15], v[84:87], v[72:75], v[0:15]
	v_add_u32_e32 v84, s2, v80
	v_mfma_f32_32x32x16_bf16 v[48:63], v[64:67], v[68:71], v[48:63]
	v_mfma_f32_32x32x16_bf16 v[32:47], v[64:67], v[72:75], v[32:47]
	ds_read_b128 v[64:67], v84 offset:16384
	v_add_u32_e32 v72, s2, v77
	ds_read_b128 v[68:71], v72
	ds_read_b128 v[72:75], v72 offset:4096
	ds_read_b128 v[84:87], v84 offset:20480
	s_waitcnt lgkmcnt(0)
	v_mfma_f32_32x32x16_bf16 v[16:31], v[84:87], v[68:71], v[16:31]
	v_mfma_f32_32x32x16_bf16 v[0:15], v[84:87], v[72:75], v[0:15]
	v_add_u32_e32 v84, s2, v78
	v_mfma_f32_32x32x16_bf16 v[48:63], v[64:67], v[68:71], v[48:63]
	v_mfma_f32_32x32x16_bf16 v[32:47], v[64:67], v[72:75], v[32:47]
	ds_read_b128 v[64:67], v84 offset:16384
	v_add_u32_e32 v72, s2, v76
	s_add_i32 s2, s9, 0xc000
	ds_read_b128 v[68:71], v72
	ds_read_b128 v[72:75], v72 offset:4096
	ds_read_b128 v[84:87], v84 offset:20480
	s_cmp_lg_u32 s9, 0x18000
	s_cselect_b32 s2, s2, 0
	s_add_i32 s2, s2, 0
	s_waitcnt vmcnt(0) lgkmcnt(0)
	s_barrier
	v_add_u32_e32 v83, s2, v83
	s_waitcnt lgkmcnt(0)
	v_mfma_f32_32x32x16_bf16 v[48:63], v[64:67], v[68:71], v[48:63]
	s_mov_b64 s[8:9], 0
	v_mfma_f32_32x32x16_bf16 v[32:47], v[64:67], v[72:75], v[32:47]
	ds_read_b128 v[64:67], v83 offset:16384
	v_mfma_f32_32x32x16_bf16 v[16:31], v[84:87], v[68:71], v[16:31]
	v_mfma_f32_32x32x16_bf16 v[0:15], v[84:87], v[72:75], v[0:15]
	v_add_u32_e32 v72, s2, v81
	ds_read_b128 v[68:71], v72
	ds_read_b128 v[72:75], v72 offset:4096
	ds_read_b128 v[84:87], v83 offset:20480
	v_add_u32_e32 v81, s2, v82
	s_waitcnt lgkmcnt(0)
	v_mfma_f32_32x32x16_bf16 v[48:63], v[64:67], v[68:71], v[48:63]
	v_mfma_f32_32x32x16_bf16 v[32:47], v[64:67], v[72:75], v[32:47]
	ds_read_b128 v[64:67], v81 offset:16384
	v_mfma_f32_32x32x16_bf16 v[16:31], v[84:87], v[68:71], v[16:31]
	v_mfma_f32_32x32x16_bf16 v[0:15], v[84:87], v[72:75], v[0:15]
	v_add_u32_e32 v72, s2, v79
	ds_read_b128 v[68:71], v72
	ds_read_b128 v[72:75], v72 offset:4096
	ds_read_b128 v[82:85], v81 offset:20480
	v_add_u32_e32 v79, s2, v80
	s_waitcnt lgkmcnt(0)
	v_mfma_f32_32x32x16_bf16 v[48:63], v[64:67], v[68:71], v[48:63]
	v_mfma_f32_32x32x16_bf16 v[32:47], v[64:67], v[72:75], v[32:47]
	ds_read_b128 v[64:67], v79 offset:16384
	v_mfma_f32_32x32x16_bf16 v[16:31], v[82:85], v[68:71], v[16:31]
	v_mfma_f32_32x32x16_bf16 v[0:15], v[82:85], v[72:75], v[0:15]
	v_add_u32_e32 v72, s2, v77
	ds_read_b128 v[68:71], v72
	ds_read_b128 v[72:75], v72 offset:4096
	ds_read_b128 v[80:83], v79 offset:20480
	v_add_u32_e32 v77, s2, v78
	s_waitcnt lgkmcnt(0)
	v_mfma_f32_32x32x16_bf16 v[48:63], v[64:67], v[68:71], v[48:63]
	v_mfma_f32_32x32x16_bf16 v[32:47], v[64:67], v[72:75], v[32:47]
	ds_read_b128 v[64:67], v77 offset:16384
	v_mfma_f32_32x32x16_bf16 v[16:31], v[80:83], v[68:71], v[16:31]
	v_mfma_f32_32x32x16_bf16 v[0:15], v[80:83], v[72:75], v[0:15]
	v_add_u32_e32 v72, s2, v76
	ds_read_b128 v[68:71], v72
	ds_read_b128 v[72:75], v72 offset:4096
	ds_read_b128 v[76:79], v77 offset:20480
	s_waitcnt vmcnt(0) lgkmcnt(0)
	s_barrier
	s_waitcnt lgkmcnt(0)
	v_mfma_f32_32x32x16_bf16 v[48:63], v[64:67], v[68:71], v[48:63]
	v_mfma_f32_32x32x16_bf16 v[32:47], v[64:67], v[72:75], v[32:47]
	v_mfma_f32_32x32x16_bf16 v[16:31], v[76:79], v[68:71], v[16:31]
	v_mfma_f32_32x32x16_bf16 v[0:15], v[76:79], v[72:75], v[0:15]

; DEV int stage_next(int s) { return (s == 2 * GS_STAGE) ? 0 : s + GS_STAGE; }
; template <int WAIT0>
; DEV void gk_main(f32x16 (&acc)[2][2], const GTile& t, int s0) {
;     ...
;   vm_wait_bar<WAIT0>();
;   int stc = s0, std_ = stage_next(stage_next(s0));
; #pragma nounroll
;   for (int kt = 0; kt < nk - 2; ++kt) {
;     GK_DMA(std_, kt + 2);
;     GK_COMPUTE(stc);
;     vm_wait_bar<6>();
;     stc = stage_next(stc); std_ = stage_next(std_);
;   }
.LBB0_846:
	s_add_i32 s10, s2, s3
	s_mov_b32 s98, s10
	s_add_i32 s11, s9, 0
	v_add_u32_e32 v253, s11, v81
	v_add_u32_e32 v252, s11, v83
	ds_read_b128 v[84:87], v252 offset:16384
	ds_read_b128 v[88:91], v253
	ds_read_b128 v[92:95], v253 offset:4096
	ds_read_b128 v[96:99], v252 offset:20480
	s_waitcnt lgkmcnt(0)
	v_add_u32_e32 v101, s11, v82
	v_add_u32_e32 v100, s11, v79
	s_add_i32 s10, s9, 0xc000
	s_cmp_lg_u32 s9, 0x18000
	s_cselect_b32 s9, s10, 0
	s_add_i32 s10, s3, 0xc000
	s_cmp_lg_u32 s3, 0x18000
	s_cselect_b32 s3, s10, 0
	s_add_i32 s8, s8, -1
	ds_read_b128 v[236:239], v101 offset:16384
	ds_read_b128 v[240:243], v100
	ds_read_b128 v[244:247], v100 offset:4096
	ds_read_b128 v[248:251], v101 offset:20480
	v_mfma_f32_32x32x16_bf16 v[48:63], v[84:87], v[88:91], v[48:63]
	v_mfma_f32_32x32x16_bf16 v[32:47], v[84:87], v[92:95], v[32:47]
	s_mov_b32 m0, s98
	v_lshl_add_u64 v[254:255], v[74:75], 0, v[120:121]
	global_load_lds_dwordx4 v[254:255], off
	v_lshl_add_u64 v[74:75], v[74:75], 0, s[94:95]
	v_mfma_f32_32x32x16_bf16 v[16:31], v[96:99], v[88:91], v[16:31]
	v_mfma_f32_32x32x16_bf16 v[0:15], v[96:99], v[92:95], v[0:15]
	s_add_i32 m0, s98, 0x2000
	v_lshl_add_u64 v[254:255], v[72:73], 0, v[120:121]
	global_load_lds_dwordx4 v[254:255], off
	v_lshl_add_u64 v[72:73], v[72:73], 0, s[94:95]
	v_add_u32_e32 v101, s11, v80
	v_add_u32_e32 v100, s11, v77
	s_waitcnt lgkmcnt(0)
	ds_read_b128 v[84:87], v101 offset:16384
	ds_read_b128 v[88:91], v100
	ds_read_b128 v[92:95], v100 offset:4096
	ds_read_b128 v[96:99], v101 offset:20480
	v_mfma_f32_32x32x16_bf16 v[48:63], v[236:239], v[240:243], v[48:63]
	v_mfma_f32_32x32x16_bf16 v[32:47], v[236:239], v[244:247], v[32:47]
	s_add_i32 m0, s98, 0x4000
	v_lshl_add_u64 v[254:255], v[70:71], 0, v[120:121]
	global_load_lds_dwordx4 v[254:255], off
	v_lshl_add_u64 v[70:71], v[70:71], 0, s[94:95]
	v_mfma_f32_32x32x16_bf16 v[16:31], v[248:251], v[240:243], v[16:31]
	v_mfma_f32_32x32x16_bf16 v[0:15], v[248:251], v[244:247], v[0:15]
	s_add_i32 m0, s98, 0x6000
	v_lshl_add_u64 v[254:255], v[68:69], 0, v[120:121]
	global_load_lds_dwordx4 v[254:255], off
	v_lshl_add_u64 v[68:69], v[68:69], 0, s[94:95]
	v_add_u32_e32 v101, s11, v78
	v_add_u32_e32 v100, s11, v76
	s_waitcnt lgkmcnt(0)
	ds_read_b128 v[236:239], v101 offset:16384
	ds_read_b128 v[240:243], v100
	ds_read_b128 v[244:247], v100 offset:4096
	ds_read_b128 v[248:251], v101 offset:20480
	v_mfma_f32_32x32x16_bf16 v[48:63], v[84:87], v[88:91], v[48:63]
	v_mfma_f32_32x32x16_bf16 v[32:47], v[84:87], v[92:95], v[32:47]
	s_add_i32 m0, s98, 0x8000
	v_lshl_add_u64 v[254:255], v[66:67], 0, v[120:121]
	global_load_lds_dwordx4 v[254:255], off
	v_lshl_add_u64 v[66:67], v[66:67], 0, s[94:95]
	v_mfma_f32_32x32x16_bf16 v[16:31], v[96:99], v[88:91], v[16:31]
	v_mfma_f32_32x32x16_bf16 v[0:15], v[96:99], v[92:95], v[0:15]
	s_add_i32 m0, s98, 0xa000
	v_lshl_add_u64 v[254:255], v[64:65], 0, v[120:121]
	global_load_lds_dwordx4 v[254:255], off
	v_lshl_add_u64 v[64:65], v[64:65], 0, s[94:95]
	s_waitcnt vmcnt(6) lgkmcnt(0)
	s_barrier
	s_waitcnt lgkmcnt(0)
	v_mfma_f32_32x32x16_bf16 v[48:63], v[236:239], v[240:243], v[48:63]
	v_mfma_f32_32x32x16_bf16 v[32:47], v[236:239], v[244:247], v[32:47]
	v_mfma_f32_32x32x16_bf16 v[16:31], v[248:251], v[240:243], v[16:31]
	v_mfma_f32_32x32x16_bf16 v[0:15], v[248:251], v[244:247], v[0:15]
	s_cmp_lg_u32 s8, 0
	s_cbranch_scc1 .LBB0_846
; DEV int stage_next(int s) { return (s == 2 * GS_STAGE) ? 0 : s + GS_STAGE; }
; template <int WAIT0>
; DEV void gk_main(f32x16 (&acc)[2][2], const GTile& t, int s0) {
;     ...
;   GK_COMPUTE(stc);
;   vm_wait_bar<0>();
;   stc = stage_next(stc);
;   GK_COMPUTE(stc);
;   vm_wait_bar<0>();
	s_add_i32 s2, s9, 0
	v_add_u32_e32 v84, s2, v83
	ds_read_b128 v[64:67], v84 offset:16384
	v_add_u32_e32 v72, s2, v81
	ds_read_b128 v[68:71], v72
	ds_read_b128 v[72:75], v72 offset:4096
	ds_read_b128 v[84:87], v84 offset:20480
	s_waitcnt lgkmcnt(0)
	v_mfma_f32_32x32x16_bf16 v[16:31], v[84:87], v[68:71], v[16:31]
	v_mfma_f32_32x32x16_bf16 v[0:15], v[84:87], v[72:75], v[0:15]
	v_add_u32_e32 v84, s2, v82
	v_mfma_f32_32x32x16_bf16 v[48:63], v[64:67], v[68:71], v[48:63]
	v_mfma_f32_32x32x16_bf16 v[32:47], v[64:67], v[72:75], v[32:47]
	ds_read_b128 v[64:67], v84 offset:16384
	v_add_u32_e32 v72, s2, v79
	ds_read_b128 v[68:71], v72
	ds_read_b128 v[72:75], v72 offset:4096
	ds_read_b128 v[84:87], v84 offset:20480
	s_waitcnt lgkmcnt(0)
	v_mfma_f32_32x32x16_bf16 v[16:31], v[84:87], v[68:71], v[16:31]
	v_mfma_f32_32x32x16_bf16 v[0:15], v[84:87], v[72:75], v[0:15]
	v_add_u32_e32 v84, s2, v80
	v_mfma_f32_32x32x16_bf16 v[48:63], v[64:67], v[68:71], v[48:63]
	v_mfma_f32_32x32x16_bf16 v[32:47], v[64:67], v[72:75], v[32:47]
	ds_read_b128 v[64:67], v84 offset:16384
	v_add_u32_e32 v72, s2, v77
	ds_read_b128 v[68:71], v72
	ds_read_b128 v[72:75], v72 offset:4096
	ds_read_b128 v[84:87], v84 offset:20480
	s_waitcnt lgkmcnt(0)
	v_mfma_f32_32x32x16_bf16 v[16:31], v[84:87], v[68:71], v[16:31]
	v_mfma_f32_32x32x16_bf16 v[0:15], v[84:87], v[72:75], v[0:15]
	v_add_u32_e32 v84, s2, v78
	v_mfma_f32_32x32x16_bf16 v[48:63], v[64:67], v[68:71], v[48:63]
	v_mfma_f32_32x32x16_bf16 v[32:47], v[64:67], v[72:75], v[32:47]
	ds_read_b128 v[64:67], v84 offset:16384
	v_add_u32_e32 v72, s2, v76
	s_add_i32 s2, s9, 0xc000
	ds_read_b128 v[68:71], v72
	ds_read_b128 v[72:75], v72 offset:4096
	ds_read_b128 v[84:87], v84 offset:20480
	s_cmp_lg_u32 s9, 0x18000
	s_cselect_b32 s2, s2, 0
	s_add_i32 s2, s2, 0
	s_waitcnt vmcnt(0) lgkmcnt(0)
	s_barrier
	v_add_u32_e32 v83, s2, v83
	s_waitcnt lgkmcnt(0)
	v_mfma_f32_32x32x16_bf16 v[48:63], v[64:67], v[68:71], v[48:63]
	v_mfma_f32_32x32x16_bf16 v[32:47], v[64:67], v[72:75], v[32:47]
	ds_read_b128 v[64:67], v83 offset:16384
	v_mfma_f32_32x32x16_bf16 v[16:31], v[84:87], v[68:71], v[16:31]
	v_mfma_f32_32x32x16_bf16 v[0:15], v[84:87], v[72:75], v[0:15]
	v_add_u32_e32 v72, s2, v81
	ds_read_b128 v[68:71], v72
	ds_read_b128 v[72:75], v72 offset:4096
	ds_read_b128 v[84:87], v83 offset:20480
	v_add_u32_e32 v81, s2, v82
	s_waitcnt lgkmcnt(0)
	v_mfma_f32_32x32x16_bf16 v[48:63], v[64:67], v[68:71], v[48:63]
	v_mfma_f32_32x32x16_bf16 v[32:47], v[64:67], v[72:75], v[32:47]
	ds_read_b128 v[64:67], v81 offset:16384
	v_mfma_f32_32x32x16_bf16 v[16:31], v[84:87], v[68:71], v[16:31]
	v_mfma_f32_32x32x16_bf16 v[0:15], v[84:87], v[72:75], v[0:15]
	v_add_u32_e32 v72, s2, v79
	ds_read_b128 v[68:71], v72
	ds_read_b128 v[72:75], v72 offset:4096
	ds_read_b128 v[82:85], v81 offset:20480
	v_add_u32_e32 v79, s2, v80
	s_waitcnt lgkmcnt(0)
	v_mfma_f32_32x32x16_bf16 v[48:63], v[64:67], v[68:71], v[48:63]
	v_mfma_f32_32x32x16_bf16 v[32:47], v[64:67], v[72:75], v[32:47]
	ds_read_b128 v[64:67], v79 offset:16384
	v_mfma_f32_32x32x16_bf16 v[16:31], v[82:85], v[68:71], v[16:31]
	v_mfma_f32_32x32x16_bf16 v[0:15], v[82:85], v[72:75], v[0:15]
	v_add_u32_e32 v72, s2, v77
	ds_read_b128 v[68:71], v72
	ds_read_b128 v[72:75], v72 offset:4096
	ds_read_b128 v[80:83], v79 offset:20480
	v_add_u32_e32 v77, s2, v78
	s_waitcnt lgkmcnt(0)
	v_mfma_f32_32x32x16_bf16 v[48:63], v[64:67], v[68:71], v[48:63]
	v_mfma_f32_32x32x16_bf16 v[32:47], v[64:67], v[72:75], v[32:47]
	ds_read_b128 v[64:67], v77 offset:16384
	v_mfma_f32_32x32x16_bf16 v[16:31], v[80:83], v[68:71], v[16:31]
	v_mfma_f32_32x32x16_bf16 v[0:15], v[80:83], v[72:75], v[0:15]
	v_add_u32_e32 v72, s2, v76
	ds_read_b128 v[68:71], v72
	ds_read_b128 v[72:75], v72 offset:4096
	ds_read_b128 v[76:79], v77 offset:20480
	s_waitcnt vmcnt(0) lgkmcnt(0)
	s_barrier
	s_waitcnt lgkmcnt(0)
	v_mfma_f32_32x32x16_bf16 v[48:63], v[64:67], v[68:71], v[48:63]
	v_mfma_f32_32x32x16_bf16 v[32:47], v[64:67], v[72:75], v[32:47]
	v_mfma_f32_32x32x16_bf16 v[16:31], v[76:79], v[68:71], v[16:31]
	v_mfma_f32_32x32x16_bf16 v[0:15], v[76:79], v[72:75], v[0:15]

; DEV int stage_next(int s) { return (s == 2 * GS_STAGE) ? 0 : s + GS_STAGE; }
; template <int WAIT0>
; DEV void gk_main(f32x16 (&acc)[2][2], const GTile& t, int s0) {
;     ...
;   vm_wait_bar<WAIT0>();
;   int stc = s0, std_ = stage_next(stage_next(s0));
; #pragma nounroll
;   for (int kt = 0; kt < nk - 2; ++kt) {
;     GK_DMA(std_, kt + 2);
;     GK_COMPUTE(stc);
;     vm_wait_bar<6>();
;     stc = stage_next(stc); std_ = stage_next(std_);
;   }
.LBB0_854:
	s_add_i32 s10, s2, s3
	s_mov_b32 s98, s10
	s_add_i32 s11, s9, 0
	v_add_u32_e32 v253, s11, v81
	v_add_u32_e32 v252, s11, v83
	ds_read_b128 v[84:87], v252 offset:16384
	ds_read_b128 v[88:91], v253
	ds_read_b128 v[92:95], v253 offset:4096
	ds_read_b128 v[96:99], v252 offset:20480
	s_waitcnt lgkmcnt(0)
	v_add_u32_e32 v101, s11, v82
	v_add_u32_e32 v100, s11, v79
	s_add_i32 s10, s9, 0xc000
	s_cmp_lg_u32 s9, 0x18000
	s_cselect_b32 s9, s10, 0
	s_add_i32 s10, s3, 0xc000
	s_cmp_lg_u32 s3, 0x18000
	s_cselect_b32 s3, s10, 0
	s_add_i32 s8, s8, -1
	ds_read_b128 v[236:239], v101 offset:16384
	ds_read_b128 v[240:243], v100
	ds_read_b128 v[244:247], v100 offset:4096
	ds_read_b128 v[248:251], v101 offset:20480
	v_mfma_f32_32x32x16_bf16 v[48:63], v[84:87], v[88:91], v[48:63]
	v_mfma_f32_32x32x16_bf16 v[32:47], v[84:87], v[92:95], v[32:47]
	s_mov_b32 m0, s98
	v_lshl_add_u64 v[254:255], v[74:75], 0, v[120:121]
	global_load_lds_dwordx4 v[254:255], off
	v_lshl_add_u64 v[74:75], v[74:75], 0, s[94:95]
	v_mfma_f32_32x32x16_bf16 v[16:31], v[96:99], v[88:91], v[16:31]
	v_mfma_f32_32x32x16_bf16 v[0:15], v[96:99], v[92:95], v[0:15]
	s_add_i32 m0, s98, 0x2000
	v_lshl_add_u64 v[254:255], v[72:73], 0, v[120:121]
	global_load_lds_dwordx4 v[254:255], off
	v_lshl_add_u64 v[72:73], v[72:73], 0, s[94:95]
	v_add_u32_e32 v101, s11, v80
	v_add_u32_e32 v100, s11, v77
	s_waitcnt lgkmcnt(0)
	ds_read_b128 v[84:87], v101 offset:16384
	ds_read_b128 v[88:91], v100
	ds_read_b128 v[92:95], v100 offset:4096
	ds_read_b128 v[96:99], v101 offset:20480
	v_mfma_f32_32x32x16_bf16 v[48:63], v[236:239], v[240:243], v[48:63]
	v_mfma_f32_32x32x16_bf16 v[32:47], v[236:239], v[244:247], v[32:47]
	s_add_i32 m0, s98, 0x4000
	v_lshl_add_u64 v[254:255], v[70:71], 0, v[120:121]
	global_load_lds_dwordx4 v[254:255], off
	v_lshl_add_u64 v[70:71], v[70:71], 0, s[94:95]
	v_mfma_f32_32x32x16_bf16 v[16:31], v[248:251], v[240:243], v[16:31]
	v_mfma_f32_32x32x16_bf16 v[0:15], v[248:251], v[244:247], v[0:15]
	s_add_i32 m0, s98, 0x6000
	v_lshl_add_u64 v[254:255], v[68:69], 0, v[120:121]
	global_load_lds_dwordx4 v[254:255], off
	v_lshl_add_u64 v[68:69], v[68:69], 0, s[94:95]
	v_add_u32_e32 v101, s11, v78
	v_add_u32_e32 v100, s11, v76
	s_waitcnt lgkmcnt(0)
	ds_read_b128 v[236:239], v101 offset:16384
	ds_read_b128 v[240:243], v100
	ds_read_b128 v[244:247], v100 offset:4096
	ds_read_b128 v[248:251], v101 offset:20480
	v_mfma_f32_32x32x16_bf16 v[48:63], v[84:87], v[88:91], v[48:63]
	v_mfma_f32_32x32x16_bf16 v[32:47], v[84:87], v[92:95], v[32:47]
	s_add_i32 m0, s98, 0x8000
	v_lshl_add_u64 v[254:255], v[66:67], 0, v[120:121]
	global_load_lds_dwordx4 v[254:255], off
	v_lshl_add_u64 v[66:67], v[66:67], 0, s[94:95]
	v_mfma_f32_32x32x16_bf16 v[16:31], v[96:99], v[88:91], v[16:31]
	v_mfma_f32_32x32x16_bf16 v[0:15], v[96:99], v[92:95], v[0:15]
	s_add_i32 m0, s98, 0xa000
	v_lshl_add_u64 v[254:255], v[64:65], 0, v[120:121]
	global_load_lds_dwordx4 v[254:255], off
	v_lshl_add_u64 v[64:65], v[64:65], 0, s[94:95]
	s_waitcnt vmcnt(6) lgkmcnt(0)
	s_barrier
	s_waitcnt lgkmcnt(0)
	v_mfma_f32_32x32x16_bf16 v[48:63], v[236:239], v[240:243], v[48:63]
	v_mfma_f32_32x32x16_bf16 v[32:47], v[236:239], v[244:247], v[32:47]
	v_mfma_f32_32x32x16_bf16 v[16:31], v[248:251], v[240:243], v[16:31]
	v_mfma_f32_32x32x16_bf16 v[0:15], v[248:251], v[244:247], v[0:15]
	s_cmp_lg_u32 s8, 0
	s_cbranch_scc1 .LBB0_854
; DEV int stage_next(int s) { return (s == 2 * GS_STAGE) ? 0 : s + GS_STAGE; }
; template <int WAIT0>
; DEV void gk_main(f32x16 (&acc)[2][2], const GTile& t, int s0) {
;     ...
;   GK_COMPUTE(stc);
;   vm_wait_bar<0>();
;   stc = stage_next(stc);
;   GK_COMPUTE(stc);
;   vm_wait_bar<0>();
; template <int WAIT_E, int WAIT_O, class TileFn, class EpiFn>
; DEV void gemm_seq(int ntiles, TileFn tf, EpiFn epi) {
;     ...
;   for (int i = 0; i < ntiles; ++i) {
;     f32x16 acc[2][2]; acc_zero(acc);
;     if (i == 0) gk_main<6>(acc, cur, s0);
;     else if (i & 1) gk_main<WAIT_O>(acc, cur, s0);
;     else gk_main<WAIT_E>(acc, cur, s0);
;     const int sn = stage_next(s0);
;     if (i + 1 < ntiles) { cur = tf(i + 1); gk_issue2(cur, sn); }
;     epi(i, acc, s0);
;     s0 = sn;
;   }
	s_add_i32 s2, s9, 0
	v_add_u32_e32 v84, s2, v83
	ds_read_b128 v[64:67], v84 offset:16384
	v_add_u32_e32 v72, s2, v81
	ds_read_b128 v[68:71], v72
	ds_read_b128 v[72:75], v72 offset:4096
	ds_read_b128 v[84:87], v84 offset:20480
	s_waitcnt lgkmcnt(0)
	v_mfma_f32_32x32x16_bf16 v[16:31], v[84:87], v[68:71], v[16:31]
	v_mfma_f32_32x32x16_bf16 v[0:15], v[84:87], v[72:75], v[0:15]
	v_add_u32_e32 v84, s2, v82
	v_mfma_f32_32x32x16_bf16 v[48:63], v[64:67], v[68:71], v[48:63]
	v_mfma_f32_32x32x16_bf16 v[32:47], v[64:67], v[72:75], v[32:47]
	ds_read_b128 v[64:67], v84 offset:16384
	v_add_u32_e32 v72, s2, v79
	ds_read_b128 v[68:71], v72
	ds_read_b128 v[72:75], v72 offset:4096
	ds_read_b128 v[84:87], v84 offset:20480
	s_waitcnt lgkmcnt(0)
	v_mfma_f32_32x32x16_bf16 v[16:31], v[84:87], v[68:71], v[16:31]
	v_mfma_f32_32x32x16_bf16 v[0:15], v[84:87], v[72:75], v[0:15]
	v_add_u32_e32 v84, s2, v80
	v_mfma_f32_32x32x16_bf16 v[48:63], v[64:67], v[68:71], v[48:63]
	v_mfma_f32_32x32x16_bf16 v[32:47], v[64:67], v[72:75], v[32:47]
	ds_read_b128 v[64:67], v84 offset:16384
	v_add_u32_e32 v72, s2, v77
	ds_read_b128 v[68:71], v72
	ds_read_b128 v[72:75], v72 offset:4096
	ds_read_b128 v[84:87], v84 offset:20480
	s_waitcnt lgkmcnt(0)
	v_mfma_f32_32x32x16_bf16 v[16:31], v[84:87], v[68:71], v[16:31]
	v_mfma_f32_32x32x16_bf16 v[0:15], v[84:87], v[72:75], v[0:15]
	v_add_u32_e32 v84, s2, v78
	v_mfma_f32_32x32x16_bf16 v[48:63], v[64:67], v[68:71], v[48:63]
	v_mfma_f32_32x32x16_bf16 v[32:47], v[64:67], v[72:75], v[32:47]
	ds_read_b128 v[64:67], v84 offset:16384
	v_add_u32_e32 v72, s2, v76
	s_add_i32 s2, s9, 0xc000
	ds_read_b128 v[68:71], v72
	ds_read_b128 v[72:75], v72 offset:4096
	ds_read_b128 v[84:87], v84 offset:20480
	s_cmp_lg_u32 s9, 0x18000
	s_cselect_b32 s2, s2, 0
	s_add_i32 s2, s2, 0
	s_waitcnt vmcnt(0) lgkmcnt(0)
	s_barrier
	v_add_u32_e32 v83, s2, v83
	s_waitcnt lgkmcnt(0)
	v_mfma_f32_32x32x16_bf16 v[48:63], v[64:67], v[68:71], v[48:63]
	v_mfma_f32_32x32x16_bf16 v[32:47], v[64:67], v[72:75], v[32:47]
	ds_read_b128 v[64:67], v83 offset:16384
	v_mfma_f32_32x32x16_bf16 v[16:31], v[84:87], v[68:71], v[16:31]
	v_mfma_f32_32x32x16_bf16 v[0:15], v[84:87], v[72:75], v[0:15]
	v_add_u32_e32 v72, s2, v81
	ds_read_b128 v[68:71], v72
	ds_read_b128 v[72:75], v72 offset:4096
	ds_read_b128 v[84:87], v83 offset:20480
	v_add_u32_e32 v81, s2, v82
	s_waitcnt lgkmcnt(0)
	v_mfma_f32_32x32x16_bf16 v[48:63], v[64:67], v[68:71], v[48:63]
	v_mfma_f32_32x32x16_bf16 v[32:47], v[64:67], v[72:75], v[32:47]
	ds_read_b128 v[64:67], v81 offset:16384
	v_mfma_f32_32x32x16_bf16 v[16:31], v[84:87], v[68:71], v[16:31]
	v_mfma_f32_32x32x16_bf16 v[0:15], v[84:87], v[72:75], v[0:15]
	v_add_u32_e32 v72, s2, v79
	ds_read_b128 v[68:71], v72
	ds_read_b128 v[72:75], v72 offset:4096
	ds_read_b128 v[82:85], v81 offset:20480
	v_add_u32_e32 v79, s2, v80
	s_waitcnt lgkmcnt(0)
	v_mfma_f32_32x32x16_bf16 v[48:63], v[64:67], v[68:71], v[48:63]
	v_mfma_f32_32x32x16_bf16 v[32:47], v[64:67], v[72:75], v[32:47]
	ds_read_b128 v[64:67], v79 offset:16384
	v_mfma_f32_32x32x16_bf16 v[16:31], v[82:85], v[68:71], v[16:31]
	v_mfma_f32_32x32x16_bf16 v[0:15], v[82:85], v[72:75], v[0:15]
	v_add_u32_e32 v72, s2, v77
	ds_read_b128 v[68:71], v72
	ds_read_b128 v[72:75], v72 offset:4096
	ds_read_b128 v[80:83], v79 offset:20480
	v_add_u32_e32 v77, s2, v78
	s_waitcnt lgkmcnt(0)
	v_mfma_f32_32x32x16_bf16 v[48:63], v[64:67], v[68:71], v[48:63]
	v_mfma_f32_32x32x16_bf16 v[32:47], v[64:67], v[72:75], v[32:47]
	ds_read_b128 v[64:67], v77 offset:16384
	v_mfma_f32_32x32x16_bf16 v[16:31], v[80:83], v[68:71], v[16:31]
	v_mfma_f32_32x32x16_bf16 v[0:15], v[80:83], v[72:75], v[0:15]
	v_add_u32_e32 v72, s2, v76
	ds_read_b128 v[68:71], v72
	ds_read_b128 v[72:75], v72 offset:4096
	ds_read_b128 v[76:79], v77 offset:20480
	s_waitcnt vmcnt(0) lgkmcnt(0)
	s_barrier
	s_waitcnt lgkmcnt(0)
	v_mfma_f32_32x32x16_bf16 v[48:63], v[64:67], v[68:71], v[48:63]
	v_mfma_f32_32x32x16_bf16 v[32:47], v[64:67], v[72:75], v[32:47]
	v_mfma_f32_32x32x16_bf16 v[16:31], v[76:79], v[68:71], v[16:31]
	v_mfma_f32_32x32x16_bf16 v[0:15], v[76:79], v[72:75], v[0:15]
	s_add_i32 s2, s19, 1
	s_cmp_eq_u32 s19, 7
	s_mov_b64 s[8:9], 0
	s_cbranch_scc1 .LBB0_850
